# static s_setprio 1 for waves 4-7 at kernel entry, all per-segment flips in the GEMM K-loops removed (strategy: one static priority raise for the younger half)
# speedup vs baseline: 1.0079x; 1.0041x over previous
; #define LAS __attribute__((address_space(3)))
; __global__ void __launch_bounds__(512, 2) k_fwd(Args a_unused) {
;     extern __shared__ __attribute__((aligned(16))) unsigned char lds_raw[];
;     LAS unsigned char* lds = (LAS unsigned char*)lds_raw;
;     int lo, hi;
;     XcdBarrier bar;
;     {   PH_IDS();
;         volatile LAS unsigned* MISC = (volatile LAS unsigned*)(lds + MISC_OFF);
;         for (int u = tid; u < (LDS_BYTES - RING_BYTES) / 4; u += 512) ((LAS unsigned*)(lds + RING_BYTES))[u] = 0u;
_Z5k_fwd4Args:
	s_mov_b64 s[6:7], s[0:1]
	v_mov_b32_e32 v2, v0
	s_load_dwordx2 s[4:5], s[6:7], 0xb8
	s_load_dword s74, s[0:1], 0xd0
	s_mov_b64 s[92:93], s[0:1]
	s_add_u32 s94, s92, 0xd0
	s_movk_i32 s0, 0x1000
	s_addc_u32 s95, s93, 0
	v_readfirstlane_b32 s1, v0
	s_nop 3
	s_lshr_b32 s1, s1, 6
	s_cmp_ge_u32 s1, 4
	s_cbranch_scc0 .Lprio_done
	s_setprio 1
.Lprio_done:
	v_cmp_gt_i32_e32 vcc, s0, v2
	s_and_saveexec_b64 s[8:9], vcc
	s_cbranch_execz .LBB0_3
	v_add_u32_e32 v1, 0xfffffe00, v2
	v_lshl_add_u32 v2, v2, 2, 0
	v_add_u32_e32 v2, 0x20000, v2
	s_mov_b64 s[10:11], 0
	v_mov_b32_e32 v3, 0
	s_movk_i32 s0, 0xdff

; #define PG8_STAGE(bufoff, gbase, voff) do { _Pragma("unroll") for (int _i = 0; _i < 2; ++_i) \
;         __builtin_amdgcn_global_load_lds((const unsigned*)((const char*)(gbase) + (voff)[_i]), (PG8_LAS unsigned*)(lds + (bufoff) + ldsw + _i * 8192), 16, 0, 0); } while (0)
; #define PG8_LDA(dst, b, h) do { _Pragma("unroll") for (int m = 0; m < 4; ++m) _Pragma("unroll") for (int k = 0; k < 2; ++k) dst[m][k] = *(const PG8_LAS bf16x8*)(lds + PG8_SA(b, h) + aoff + m * 2048 + k * 1024); } while (0)
; #define PG8_LDB(dst, b, h) do { _Pragma("unroll") for (int n = 0; n < 2; ++n) _Pragma("unroll") for (int k = 0; k < 2; ++k) dst[n][k] = *(const PG8_LAS bf16x8*)(lds + PG8_SB(b, h) + boff + n * 2048 + k * 1024); } while (0)
; #define PG8_WAIT_V(n) asm volatile("s_waitcnt vmcnt(" #n ")" ::: "memory")
; #define PG8_WAIT_L(n) asm volatile("s_waitcnt lgkmcnt(" #n ")" ::: "memory")
; #define PG8_BAR __builtin_amdgcn_s_barrier()
; #define PG8_SCHED __builtin_amdgcn_sched_barrier(0)
; template <class Epi, class Sched, bool ALIGN_EPI = false, bool SP2 = false>
; __device__ __forceinline__ void gemm_phase(PG8_LAS unsigned char* lds, const Gemm g, const Sched& S, const Epi& E) {
;     ...
;             PG8_LDB(B0, 0, 0); PG8_LDB(B1, 0, 1); PG8_SCHED; PG8_LDA(At, 0, 0); PG8_STAGE(PG8_SA(1, 1), a1 + hstep, voffA);
;             PG8_WAIT_V(8); PG8_WAIT_L(0); PG8_BAR; PG8_MMA(0, 0, At, B0); PG8_MMA(0, 1, At, B1); PG8_BAR; PG8_SCHED;
;             PG8_LDA(At, 0, 1); PG8_STAGE(PG8_SB(0, 0), b2, voffB); PG8_STAGE(PG8_SB(0, 1), b2 + hstep, voffB); PG8_STAGE(PG8_SA(0, 0), a2, voffA);
;             PG8_WAIT_V(8); PG8_WAIT_L(0); PG8_BAR; PG8_MMA(1, 0, At, B0); PG8_MMA(1, 1, At, B1); PG8_BAR; PG8_SCHED;
.LBB0_259:
	ds_read_b128 v[130:133], v202
	ds_read_b128 v[134:137], v202 offset:1024
	ds_read_b128 v[138:141], v202 offset:2048
	ds_read_b128 v[142:145], v202 offset:3072
	ds_read_b128 v[172:175], v203
	ds_read_b128 v[176:179], v203 offset:1024
	ds_read_b128 v[180:183], v203 offset:2048
	ds_read_b128 v[184:187], v203 offset:3072
	s_add_u32 s52, s50, 0xfff00080
	s_addc_u32 s53, s51, -1
	s_cmp_eq_u32 s49, 60
	s_cselect_b32 s55, s1, s53
	s_cselect_b32 s54, s4, s52
	s_cselect_b32 s53, s5, s43
	s_cselect_b32 s52, s33, s41
	v_lshl_add_u64 v[192:193], s[50:51], 0, v[162:163]
	s_add_i32 m0, s60, 0xc000
	ds_read_b128 v[188:191], v204
	ds_read_b128 v[208:211], v204 offset:1024
	ds_read_b128 v[212:215], v204 offset:2048
	ds_read_b128 v[216:219], v204 offset:3072
	ds_read_b128 v[220:223], v204 offset:4096
	ds_read_b128 v[224:227], v204 offset:5120
	ds_read_b128 v[228:231], v204 offset:6144
	ds_read_b128 v[232:235], v204 offset:7168
	global_load_lds_dwordx4 v[192:193], off
	v_lshl_add_u64 v[192:193], s[50:51], 0, v[164:165]
	s_add_i32 m0, s60, 0xe000
	s_nop 0
	global_load_lds_dwordx4 v[192:193], off
	s_waitcnt vmcnt(8)
	s_waitcnt lgkmcnt(0)
	s_barrier
	s_waitcnt lgkmcnt(0)
	v_mfma_f32_16x16x32_bf16 v[126:129], v[130:133], v[188:191], v[126:129]
	v_mfma_f32_16x16x32_bf16 v[122:125], v[138:141], v[188:191], v[122:125]
	v_mfma_f32_16x16x32_bf16 v[110:113], v[130:133], v[212:215], v[110:113]
	v_mfma_f32_16x16x32_bf16 v[106:109], v[138:141], v[212:215], v[106:109]
	v_mfma_f32_16x16x32_bf16 v[94:97], v[130:133], v[220:223], v[94:97]
	v_mfma_f32_16x16x32_bf16 v[90:93], v[138:141], v[220:223], v[90:93]
	v_mfma_f32_16x16x32_bf16 v[78:81], v[130:133], v[228:231], v[78:81]
	v_mfma_f32_16x16x32_bf16 v[74:77], v[138:141], v[228:231], v[74:77]
	v_mfma_f32_16x16x32_bf16 v[126:129], v[134:137], v[208:211], v[126:129]
	v_mfma_f32_16x16x32_bf16 v[122:125], v[142:145], v[208:211], v[122:125]
	v_mfma_f32_16x16x32_bf16 v[110:113], v[134:137], v[216:219], v[110:113]
	v_mfma_f32_16x16x32_bf16 v[106:109], v[142:145], v[216:219], v[106:109]
	v_mfma_f32_16x16x32_bf16 v[94:97], v[134:137], v[224:227], v[94:97]
	v_mfma_f32_16x16x32_bf16 v[90:93], v[142:145], v[224:227], v[90:93]
	v_mfma_f32_16x16x32_bf16 v[78:81], v[134:137], v[232:235], v[78:81]
	v_mfma_f32_16x16x32_bf16 v[74:77], v[142:145], v[232:235], v[74:77]
	v_mfma_f32_16x16x32_bf16 v[118:121], v[172:175], v[188:191], v[118:121]
	v_mfma_f32_16x16x32_bf16 v[114:117], v[180:183], v[188:191], v[114:117]
	v_mfma_f32_16x16x32_bf16 v[102:105], v[172:175], v[212:215], v[102:105]
	v_mfma_f32_16x16x32_bf16 v[98:101], v[180:183], v[212:215], v[98:101]
	v_mfma_f32_16x16x32_bf16 v[86:89], v[172:175], v[220:223], v[86:89]
	v_mfma_f32_16x16x32_bf16 v[82:85], v[180:183], v[220:223], v[82:85]
	v_mfma_f32_16x16x32_bf16 v[70:73], v[172:175], v[228:231], v[70:73]
	v_mfma_f32_16x16x32_bf16 v[66:69], v[180:183], v[228:231], v[66:69]
	v_mfma_f32_16x16x32_bf16 v[118:121], v[176:179], v[208:211], v[118:121]
	v_mfma_f32_16x16x32_bf16 v[114:117], v[184:187], v[208:211], v[114:117]
	v_mfma_f32_16x16x32_bf16 v[102:105], v[176:179], v[216:219], v[102:105]
	v_mfma_f32_16x16x32_bf16 v[98:101], v[184:187], v[216:219], v[98:101]
	v_mfma_f32_16x16x32_bf16 v[86:89], v[176:179], v[224:227], v[86:89]
	v_mfma_f32_16x16x32_bf16 v[82:85], v[184:187], v[224:227], v[82:85]
	v_mfma_f32_16x16x32_bf16 v[70:73], v[176:179], v[232:235], v[70:73]
	v_mfma_f32_16x16x32_bf16 v[66:69], v[184:187], v[232:235], v[66:69]
	s_barrier
	s_add_i32 s87, s70, s59
	v_lshl_add_u64 v[192:193], s[52:53], 0, v[146:147]
	s_mov_b32 m0, s87
	ds_read_b128 v[188:191], v204 offset:16384
	ds_read_b128 v[208:211], v204 offset:17408
	ds_read_b128 v[212:215], v204 offset:18432
	ds_read_b128 v[216:219], v204 offset:19456
	ds_read_b128 v[220:223], v204 offset:20480
	ds_read_b128 v[224:227], v204 offset:21504
	ds_read_b128 v[228:231], v204 offset:22528
	ds_read_b128 v[232:235], v204 offset:23552
	global_load_lds_dwordx4 v[192:193], off
	s_add_i32 m0, s87, 0x2000
	s_add_u32 s88, s52, 0x100000
	v_lshl_add_u64 v[236:237], s[52:53], 0, v[148:149]
	s_addc_u32 s89, s53, 0
	s_add_i32 s87, s71, s59
	global_load_lds_dwordx4 v[236:237], off
	v_lshl_add_u64 v[238:239], s[88:89], 0, v[146:147]
	s_mov_b32 m0, s87
	v_lshl_add_u64 v[240:241], s[54:55], 0, v[148:149]
	global_load_lds_dwordx4 v[238:239], off
	v_lshl_add_u64 v[238:239], s[88:89], 0, v[148:149]
	s_add_i32 m0, s87, 0x2000
	s_nop 0
	global_load_lds_dwordx4 v[238:239], off
	v_lshl_add_u64 v[238:239], s[54:55], 0, v[146:147]
	s_mov_b32 m0, s60
	s_nop 0
	global_load_lds_dwordx4 v[238:239], off
	s_mov_b32 m0, s61
	s_nop 0
	global_load_lds_dwordx4 v[240:241], off
	s_waitcnt vmcnt(8)
	s_waitcnt lgkmcnt(0)
	s_barrier
; #define PG8_STAGE(bufoff, gbase, voff) do { _Pragma("unroll") for (int _i = 0; _i < 2; ++_i) \
;         __builtin_amdgcn_global_load_lds((const unsigned*)((const char*)(gbase) + (voff)[_i]), (PG8_LAS unsigned*)(lds + (bufoff) + ldsw + _i * 8192), 16, 0, 0); } while (0)
; #define PG8_LDA(dst, b, h) do { _Pragma("unroll") for (int m = 0; m < 4; ++m) _Pragma("unroll") for (int k = 0; k < 2; ++k) dst[m][k] = *(const PG8_LAS bf16x8*)(lds + PG8_SA(b, h) + aoff + m * 2048 + k * 1024); } while (0)
; #define PG8_LDB(dst, b, h) do { _Pragma("unroll") for (int n = 0; n < 2; ++n) _Pragma("unroll") for (int k = 0; k < 2; ++k) dst[n][k] = *(const PG8_LAS bf16x8*)(lds + PG8_SB(b, h) + boff + n * 2048 + k * 1024); } while (0)
; #define PG8_WAIT_V(n) asm volatile("s_waitcnt vmcnt(" #n ")" ::: "memory")
; #define PG8_WAIT_L(n) asm volatile("s_waitcnt lgkmcnt(" #n ")" ::: "memory")
; #define PG8_BAR __builtin_amdgcn_s_barrier()
; #define PG8_SCHED __builtin_amdgcn_sched_barrier(0)
; template <class Epi, class Sched, bool ALIGN_EPI = false, bool SP2 = false>
; __device__ __forceinline__ void gemm_phase(PG8_LAS unsigned char* lds, const Gemm g, const Sched& S, const Epi& E) {
;     ...
;             PG8_WAIT_V(8); PG8_WAIT_L(0); PG8_BAR; PG8_MMA(1, 0, At, B0); PG8_MMA(1, 1, At, B1); PG8_BAR; PG8_SCHED;
;             PG8_LDB(B0, 1, 0); PG8_LDB(B1, 1, 1); PG8_SCHED; PG8_LDA(At, 1, 0); PG8_STAGE(PG8_SA(0, 1), a2 + hstep, voffA);
;             PG8_WAIT_V(8); PG8_WAIT_L(0); PG8_BAR; PG8_MMA(0, 0, At, B0); PG8_MMA(0, 1, At, B1); PG8_BAR; PG8_SCHED;
	s_waitcnt lgkmcnt(0)
	v_mfma_f32_16x16x32_bf16 v[62:65], v[130:133], v[188:191], v[62:65]
	v_mfma_f32_16x16x32_bf16 v[58:61], v[138:141], v[188:191], v[58:61]
	v_mfma_f32_16x16x32_bf16 v[46:49], v[130:133], v[212:215], v[46:49]
	v_mfma_f32_16x16x32_bf16 v[42:45], v[138:141], v[212:215], v[42:45]
	v_mfma_f32_16x16x32_bf16 v[30:33], v[130:133], v[220:223], v[30:33]
	v_mfma_f32_16x16x32_bf16 v[26:29], v[138:141], v[220:223], v[26:29]
	v_mfma_f32_16x16x32_bf16 v[14:17], v[130:133], v[228:231], v[14:17]
	v_mfma_f32_16x16x32_bf16 v[10:13], v[138:141], v[228:231], v[10:13]
	v_mfma_f32_16x16x32_bf16 v[62:65], v[134:137], v[208:211], v[62:65]
	v_mfma_f32_16x16x32_bf16 v[58:61], v[142:145], v[208:211], v[58:61]
	v_mfma_f32_16x16x32_bf16 v[46:49], v[134:137], v[216:219], v[46:49]
	v_mfma_f32_16x16x32_bf16 v[42:45], v[142:145], v[216:219], v[42:45]
	v_mfma_f32_16x16x32_bf16 v[30:33], v[134:137], v[224:227], v[30:33]
	v_mfma_f32_16x16x32_bf16 v[26:29], v[142:145], v[224:227], v[26:29]
	v_mfma_f32_16x16x32_bf16 v[14:17], v[134:137], v[232:235], v[14:17]
	v_mfma_f32_16x16x32_bf16 v[10:13], v[142:145], v[232:235], v[10:13]
	v_mfma_f32_16x16x32_bf16 v[54:57], v[172:175], v[188:191], v[54:57]
	v_mfma_f32_16x16x32_bf16 v[50:53], v[180:183], v[188:191], v[50:53]
	v_mfma_f32_16x16x32_bf16 v[38:41], v[172:175], v[212:215], v[38:41]
	v_mfma_f32_16x16x32_bf16 v[34:37], v[180:183], v[212:215], v[34:37]
	v_mfma_f32_16x16x32_bf16 v[22:25], v[172:175], v[220:223], v[22:25]
	v_mfma_f32_16x16x32_bf16 v[18:21], v[180:183], v[220:223], v[18:21]
	v_mfma_f32_16x16x32_bf16 v[6:9], v[172:175], v[228:231], v[6:9]
	v_mfma_f32_16x16x32_bf16 v[2:5], v[180:183], v[228:231], v[2:5]
	v_mfma_f32_16x16x32_bf16 v[54:57], v[176:179], v[208:211], v[54:57]
	v_mfma_f32_16x16x32_bf16 v[50:53], v[184:187], v[208:211], v[50:53]
	v_mfma_f32_16x16x32_bf16 v[38:41], v[176:179], v[216:219], v[38:41]
	v_mfma_f32_16x16x32_bf16 v[34:37], v[184:187], v[216:219], v[34:37]
	v_mfma_f32_16x16x32_bf16 v[22:25], v[176:179], v[224:227], v[22:25]
	v_mfma_f32_16x16x32_bf16 v[18:21], v[184:187], v[224:227], v[18:21]
	v_mfma_f32_16x16x32_bf16 v[6:9], v[176:179], v[232:235], v[6:9]
	v_mfma_f32_16x16x32_bf16 v[2:5], v[184:187], v[232:235], v[2:5]
	s_barrier
	s_add_i32 s87, 0, 0x18000
	s_add_i32 s88, 0, 0x1c000
	v_add_u32_e32 v142, s87, v200
	v_add_u32_e32 v150, s88, v200
	ds_read_b128 v[130:133], v142
	ds_read_b128 v[134:137], v142 offset:1024
	ds_read_b128 v[138:141], v142 offset:2048
	ds_read_b128 v[142:145], v142 offset:3072
	ds_read_b128 v[172:175], v150
	ds_read_b128 v[176:179], v150 offset:1024
	ds_read_b128 v[180:183], v150 offset:2048
	ds_read_b128 v[184:187], v150 offset:3072
	s_add_u32 s54, s54, 0x100000
	s_addc_u32 s55, s55, 0
	s_mov_b32 m0, s62
	v_lshl_add_u64 v[242:243], s[54:55], 0, v[146:147]
	ds_read_b128 v[188:191], v204 offset:32768
	ds_read_b128 v[208:211], v204 offset:33792
	ds_read_b128 v[212:215], v204 offset:34816
	ds_read_b128 v[216:219], v204 offset:35840
	ds_read_b128 v[220:223], v204 offset:36864
	ds_read_b128 v[224:227], v204 offset:37888
	ds_read_b128 v[228:231], v204 offset:38912
	ds_read_b128 v[232:235], v204 offset:39936
	global_load_lds_dwordx4 v[242:243], off
	v_lshl_add_u64 v[242:243], s[54:55], 0, v[148:149]
	s_mov_b32 m0, s63
	s_nop 0
	global_load_lds_dwordx4 v[242:243], off
	s_waitcnt vmcnt(8)
	s_waitcnt lgkmcnt(0)
	s_barrier
	s_waitcnt lgkmcnt(0)
	v_mfma_f32_16x16x32_bf16 v[126:129], v[130:133], v[188:191], v[126:129]
	v_mfma_f32_16x16x32_bf16 v[122:125], v[138:141], v[188:191], v[122:125]
	v_mfma_f32_16x16x32_bf16 v[110:113], v[130:133], v[212:215], v[110:113]
	v_mfma_f32_16x16x32_bf16 v[106:109], v[138:141], v[212:215], v[106:109]
	v_mfma_f32_16x16x32_bf16 v[94:97], v[130:133], v[220:223], v[94:97]
	v_mfma_f32_16x16x32_bf16 v[90:93], v[138:141], v[220:223], v[90:93]
	v_mfma_f32_16x16x32_bf16 v[78:81], v[130:133], v[228:231], v[78:81]
	v_mfma_f32_16x16x32_bf16 v[74:77], v[138:141], v[228:231], v[74:77]
	v_mfma_f32_16x16x32_bf16 v[126:129], v[134:137], v[208:211], v[126:129]
	v_mfma_f32_16x16x32_bf16 v[122:125], v[142:145], v[208:211], v[122:125]
	v_mfma_f32_16x16x32_bf16 v[110:113], v[134:137], v[216:219], v[110:113]
	v_mfma_f32_16x16x32_bf16 v[106:109], v[142:145], v[216:219], v[106:109]
	v_mfma_f32_16x16x32_bf16 v[94:97], v[134:137], v[224:227], v[94:97]
	v_mfma_f32_16x16x32_bf16 v[90:93], v[142:145], v[224:227], v[90:93]
	v_mfma_f32_16x16x32_bf16 v[78:81], v[134:137], v[232:235], v[78:81]
	v_mfma_f32_16x16x32_bf16 v[74:77], v[142:145], v[232:235], v[74:77]
	v_mfma_f32_16x16x32_bf16 v[118:121], v[172:175], v[188:191], v[118:121]
	v_mfma_f32_16x16x32_bf16 v[114:117], v[180:183], v[188:191], v[114:117]
	v_mfma_f32_16x16x32_bf16 v[102:105], v[172:175], v[212:215], v[102:105]
	v_mfma_f32_16x16x32_bf16 v[98:101], v[180:183], v[212:215], v[98:101]
	v_mfma_f32_16x16x32_bf16 v[86:89], v[172:175], v[220:223], v[86:89]
	v_mfma_f32_16x16x32_bf16 v[82:85], v[180:183], v[220:223], v[82:85]
	v_mfma_f32_16x16x32_bf16 v[70:73], v[172:175], v[228:231], v[70:73]
	v_mfma_f32_16x16x32_bf16 v[66:69], v[180:183], v[228:231], v[66:69]
	v_mfma_f32_16x16x32_bf16 v[118:121], v[176:179], v[208:211], v[118:121]
	v_mfma_f32_16x16x32_bf16 v[114:117], v[184:187], v[208:211], v[114:117]
	v_mfma_f32_16x16x32_bf16 v[102:105], v[176:179], v[216:219], v[102:105]
	v_mfma_f32_16x16x32_bf16 v[98:101], v[184:187], v[216:219], v[98:101]
	v_mfma_f32_16x16x32_bf16 v[86:89], v[176:179], v[224:227], v[86:89]
	v_mfma_f32_16x16x32_bf16 v[82:85], v[184:187], v[224:227], v[82:85]
	v_mfma_f32_16x16x32_bf16 v[70:73], v[176:179], v[232:235], v[70:73]
	v_mfma_f32_16x16x32_bf16 v[66:69], v[184:187], v[232:235], v[66:69]
	s_barrier
; #define PG8_STAGE(bufoff, gbase, voff) do { _Pragma("unroll") for (int _i = 0; _i < 2; ++_i) \
;         __builtin_amdgcn_global_load_lds((const unsigned*)((const char*)(gbase) + (voff)[_i]), (PG8_LAS unsigned*)(lds + (bufoff) + ldsw + _i * 8192), 16, 0, 0); } while (0)
; #define PG8_LDA(dst, b, h) do { _Pragma("unroll") for (int m = 0; m < 4; ++m) _Pragma("unroll") for (int k = 0; k < 2; ++k) dst[m][k] = *(const PG8_LAS bf16x8*)(lds + PG8_SA(b, h) + aoff + m * 2048 + k * 1024); } while (0)
; #define PG8_WAIT_V(n) asm volatile("s_waitcnt vmcnt(" #n ")" ::: "memory")
; #define PG8_WAIT_L(n) asm volatile("s_waitcnt lgkmcnt(" #n ")" ::: "memory")
; #define PG8_BAR __builtin_amdgcn_s_barrier()
; #define PG8_SCHED __builtin_amdgcn_sched_barrier(0)
; template <class Epi, class Sched, bool ALIGN_EPI = false, bool SP2 = false>
; __device__ __forceinline__ void gemm_phase(PG8_LAS unsigned char* lds, const Gemm g, const Sched& S, const Epi& E) {
;     ...
;         for (int t = 0; t < nt; t += 2) {
;     ...
;             PG8_LDA(At, 1, 1); PG8_STAGE(PG8_SB(1, 0), b3, voffB); PG8_STAGE(PG8_SB(1, 1), b3 + hstep, voffB); PG8_STAGE(PG8_SA(1, 0), a3, voffA);
;             PG8_WAIT_V(8); PG8_WAIT_L(0); PG8_BAR; PG8_MMA(1, 0, At, B0); PG8_MMA(1, 1, At, B1); PG8_BAR; PG8_SCHED;
	s_add_i32 s54, s87, s59
	v_lshl_add_u64 v[192:193], v[192:193], 0, s[24:25]
	s_mov_b32 m0, s54
	ds_read_b128 v[188:191], v204 offset:49152
	ds_read_b128 v[208:211], v204 offset:50176
	ds_read_b128 v[212:215], v204 offset:51200
	ds_read_b128 v[216:219], v204 offset:52224
	ds_read_b128 v[220:223], v204 offset:53248
	ds_read_b128 v[224:227], v204 offset:54272
	ds_read_b128 v[228:231], v204 offset:55296
	ds_read_b128 v[232:235], v204 offset:56320
	global_load_lds_dwordx4 v[192:193], off
	s_add_i32 m0, s54, 0x2000
	s_add_u32 s52, s52, 0x100080
	v_lshl_add_u64 v[192:193], v[236:237], 0, s[24:25]
	s_addc_u32 s53, s53, 0
	s_add_i32 s54, s88, s59
	global_load_lds_dwordx4 v[192:193], off
	v_lshl_add_u64 v[192:193], s[52:53], 0, v[146:147]
	s_mov_b32 m0, s54
	s_nop 0
	global_load_lds_dwordx4 v[192:193], off
	v_lshl_add_u64 v[192:193], s[52:53], 0, v[148:149]
	s_add_i32 m0, s54, 0x2000
	s_nop 0
	global_load_lds_dwordx4 v[192:193], off
	v_lshl_add_u64 v[192:193], v[238:239], 0, s[24:25]
	s_mov_b32 m0, s64
	s_nop 0
	global_load_lds_dwordx4 v[192:193], off
	v_lshl_add_u64 v[192:193], v[240:241], 0, s[24:25]
	s_mov_b32 m0, s65
	s_nop 0
	global_load_lds_dwordx4 v[192:193], off
	s_waitcnt vmcnt(8)
	s_waitcnt lgkmcnt(0)
	s_barrier
	s_waitcnt lgkmcnt(0)
	v_mfma_f32_16x16x32_bf16 v[62:65], v[130:133], v[188:191], v[62:65]
	v_mfma_f32_16x16x32_bf16 v[58:61], v[138:141], v[188:191], v[58:61]
	v_mfma_f32_16x16x32_bf16 v[46:49], v[130:133], v[212:215], v[46:49]
	v_mfma_f32_16x16x32_bf16 v[42:45], v[138:141], v[212:215], v[42:45]
	v_mfma_f32_16x16x32_bf16 v[30:33], v[130:133], v[220:223], v[30:33]
	v_mfma_f32_16x16x32_bf16 v[26:29], v[138:141], v[220:223], v[26:29]
	v_mfma_f32_16x16x32_bf16 v[14:17], v[130:133], v[228:231], v[14:17]
	v_mfma_f32_16x16x32_bf16 v[10:13], v[138:141], v[228:231], v[10:13]
	v_mfma_f32_16x16x32_bf16 v[62:65], v[134:137], v[208:211], v[62:65]
	v_mfma_f32_16x16x32_bf16 v[58:61], v[142:145], v[208:211], v[58:61]
	v_mfma_f32_16x16x32_bf16 v[46:49], v[134:137], v[216:219], v[46:49]
	v_mfma_f32_16x16x32_bf16 v[42:45], v[142:145], v[216:219], v[42:45]
	v_mfma_f32_16x16x32_bf16 v[30:33], v[134:137], v[224:227], v[30:33]
	v_mfma_f32_16x16x32_bf16 v[26:29], v[142:145], v[224:227], v[26:29]
	v_mfma_f32_16x16x32_bf16 v[14:17], v[134:137], v[232:235], v[14:17]
	v_mfma_f32_16x16x32_bf16 v[10:13], v[142:145], v[232:235], v[10:13]
	v_mfma_f32_16x16x32_bf16 v[54:57], v[172:175], v[188:191], v[54:57]
	v_mfma_f32_16x16x32_bf16 v[50:53], v[180:183], v[188:191], v[50:53]
	v_mfma_f32_16x16x32_bf16 v[38:41], v[172:175], v[212:215], v[38:41]
	v_mfma_f32_16x16x32_bf16 v[34:37], v[180:183], v[212:215], v[34:37]
	v_mfma_f32_16x16x32_bf16 v[22:25], v[172:175], v[220:223], v[22:25]
	v_mfma_f32_16x16x32_bf16 v[18:21], v[180:183], v[220:223], v[18:21]
	v_mfma_f32_16x16x32_bf16 v[6:9], v[172:175], v[228:231], v[6:9]
	v_mfma_f32_16x16x32_bf16 v[2:5], v[180:183], v[228:231], v[2:5]
	v_mfma_f32_16x16x32_bf16 v[54:57], v[176:179], v[208:211], v[54:57]
	v_mfma_f32_16x16x32_bf16 v[50:53], v[184:187], v[208:211], v[50:53]
	v_mfma_f32_16x16x32_bf16 v[38:41], v[176:179], v[216:219], v[38:41]
	v_mfma_f32_16x16x32_bf16 v[34:37], v[184:187], v[216:219], v[34:37]
	v_mfma_f32_16x16x32_bf16 v[22:25], v[176:179], v[224:227], v[22:25]
	v_mfma_f32_16x16x32_bf16 v[18:21], v[184:187], v[224:227], v[18:21]
	v_mfma_f32_16x16x32_bf16 v[6:9], v[176:179], v[232:235], v[6:9]
	v_mfma_f32_16x16x32_bf16 v[2:5], v[184:187], v[232:235], v[2:5]
	s_barrier
	s_add_i32 s49, s49, 2
	s_add_u32 s50, s50, 0x100
	s_addc_u32 s51, s51, 0
	s_add_u32 s41, s41, 0x100
	s_addc_u32 s43, s43, 0
	s_cmp_gt_u32 s49, 61
	s_cbranch_scc0 .LBB0_259
	s_and_b64 vcc, exec, s[26:27]
	s_cbranch_vccnz .LBB0_264
	v_lshl_add_u32 v172, s48, 8, v199
	s_cmp_gt_i32 s12, 8
	s_mov_b64 s[48:49], -1
	s_cbranch_scc1 .LBB0_265

; #define PG8_STAGE(bufoff, gbase, voff) do { _Pragma("unroll") for (int _i = 0; _i < 2; ++_i) \
;         __builtin_amdgcn_global_load_lds((const unsigned*)((const char*)(gbase) + (voff)[_i]), (PG8_LAS unsigned*)(lds + (bufoff) + ldsw + _i * 8192), 16, 0, 0); } while (0)
; #define PG8_LDA(dst, b, h) do { _Pragma("unroll") for (int m = 0; m < 4; ++m) _Pragma("unroll") for (int k = 0; k < 2; ++k) dst[m][k] = *(const PG8_LAS bf16x8*)(lds + PG8_SA(b, h) + aoff + m * 2048 + k * 1024); } while (0)
; #define PG8_LDB(dst, b, h) do { _Pragma("unroll") for (int n = 0; n < 2; ++n) _Pragma("unroll") for (int k = 0; k < 2; ++k) dst[n][k] = *(const PG8_LAS bf16x8*)(lds + PG8_SB(b, h) + boff + n * 2048 + k * 1024); } while (0)
; #define PG8_WAIT_V(n) asm volatile("s_waitcnt vmcnt(" #n ")" ::: "memory")
; #define PG8_WAIT_L(n) asm volatile("s_waitcnt lgkmcnt(" #n ")" ::: "memory")
; #define PG8_BAR __builtin_amdgcn_s_barrier()
; #define PG8_SCHED __builtin_amdgcn_sched_barrier(0)
; template <class Epi, class Sched, bool ALIGN_EPI = false, bool SP2 = false>
; __device__ __forceinline__ void gemm_phase(PG8_LAS unsigned char* lds, const Gemm g, const Sched& S, const Epi& E) {
;     ...
;                 for (int n = 0; n < 2; ++n) acc[a][b][m][n] = (f32x4){0.f, 0.f, 0.f, 0.f};
;     ...
;             PG8_LDB(B0, 0, 0); PG8_LDB(B1, 0, 1); PG8_SCHED; PG8_LDA(At, 0, 0); PG8_STAGE(PG8_SA(1, 1), a1 + hstep, voffA);
;             PG8_WAIT_V(8); PG8_WAIT_L(0); PG8_BAR; PG8_MMA(0, 0, At, B0); PG8_MMA(0, 1, At, B1); PG8_BAR; PG8_SCHED;
;             PG8_LDA(At, 0, 1); PG8_STAGE(PG8_SB(0, 0), b2, voffB); PG8_STAGE(PG8_SB(0, 1), b2 + hstep, voffB); PG8_STAGE(PG8_SA(0, 0), a2, voffA);
;             PG8_WAIT_V(8); PG8_WAIT_L(0); PG8_BAR; PG8_MMA(1, 0, At, B0); PG8_MMA(1, 1, At, B1); PG8_BAR; PG8_SCHED;
.LBB0_435:
	ds_read_b128 v[2:5], v136
	ds_read_b128 v[6:9], v136 offset:1024
	ds_read_b128 v[10:13], v136 offset:2048
	ds_read_b128 v[14:17], v136 offset:3072
	ds_read_b128 v[18:21], v137
	ds_read_b128 v[22:25], v137 offset:1024
	ds_read_b128 v[26:29], v137 offset:2048
	ds_read_b128 v[30:33], v137 offset:3072
	s_ashr_i32 s35, s34, 31
	s_lshl_b64 s[38:39], s[34:35], 17
	s_add_u32 s38, s1, s38
	s_addc_u32 s39, s3, s39
	s_and_b64 s[42:43], s[40:41], exec
	s_cselect_b32 s53, s39, s47
	s_cselect_b32 s52, s38, s46
	s_ashr_i32 s37, s36, 31
	s_lshl_b64 s[42:43], s[36:37], 17
	s_add_u32 s42, s4, s42
	s_addc_u32 s43, s5, s43
	s_and_b64 s[50:51], s[40:41], exec
	s_cselect_b32 s51, s43, s49
	s_cselect_b32 s50, s42, s48
	s_add_u32 s70, s46, 0x10080
	s_addc_u32 s71, s47, 0
	s_add_i32 s75, s45, 0xc000
	v_lshl_add_u64 v[66:67], s[70:71], 0, v[130:131]
	s_mov_b32 m0, s75
	s_add_i32 s35, s45, 0xe000
	ds_read_b128 v[34:37], v138
	ds_read_b128 v[38:41], v138 offset:1024
	ds_read_b128 v[42:45], v138 offset:2048
	ds_read_b128 v[46:49], v138 offset:3072
	ds_read_b128 v[50:53], v138 offset:4096
	ds_read_b128 v[54:57], v138 offset:5120
	ds_read_b128 v[58:61], v138 offset:6144
	ds_read_b128 v[62:65], v138 offset:7168
	global_load_lds_dwordx4 v[66:67], off
	v_lshl_add_u64 v[66:67], s[70:71], 0, v[132:133]
	s_mov_b32 m0, s35
	s_nop 0
	global_load_lds_dwordx4 v[66:67], off
	s_waitcnt vmcnt(8)
	s_waitcnt lgkmcnt(0)
	s_barrier
	s_waitcnt lgkmcnt(0)
	v_mfma_f32_16x16x32_bf16 v[66:69], v[2:5], v[34:37], 0
	v_mfma_f32_16x16x32_bf16 v[70:73], v[10:13], v[34:37], 0
	v_mfma_f32_16x16x32_bf16 v[74:77], v[2:5], v[42:45], 0
	v_mfma_f32_16x16x32_bf16 v[78:81], v[10:13], v[42:45], 0
	v_mfma_f32_16x16x32_bf16 v[82:85], v[2:5], v[50:53], 0
	v_mfma_f32_16x16x32_bf16 v[86:89], v[10:13], v[50:53], 0
	v_mfma_f32_16x16x32_bf16 v[90:93], v[2:5], v[58:61], 0
	v_mfma_f32_16x16x32_bf16 v[94:97], v[10:13], v[58:61], 0
	v_mfma_f32_16x16x32_bf16 v[66:69], v[6:9], v[38:41], v[66:69]
	v_mfma_f32_16x16x32_bf16 v[70:73], v[14:17], v[38:41], v[70:73]
	v_mfma_f32_16x16x32_bf16 v[74:77], v[6:9], v[46:49], v[74:77]
	v_mfma_f32_16x16x32_bf16 v[78:81], v[14:17], v[46:49], v[78:81]
	v_mfma_f32_16x16x32_bf16 v[82:85], v[6:9], v[54:57], v[82:85]
	v_mfma_f32_16x16x32_bf16 v[86:89], v[14:17], v[54:57], v[86:89]
	v_mfma_f32_16x16x32_bf16 v[90:93], v[6:9], v[62:65], v[90:93]
	v_mfma_f32_16x16x32_bf16 v[94:97], v[14:17], v[62:65], v[94:97]
	v_mfma_f32_16x16x32_bf16 v[98:101], v[18:21], v[34:37], 0
	v_mfma_f32_16x16x32_bf16 v[34:37], v[26:29], v[34:37], 0
	v_mfma_f32_16x16x32_bf16 v[98:101], v[22:25], v[38:41], v[98:101]
	v_mfma_f32_16x16x32_bf16 v[34:37], v[30:33], v[38:41], v[34:37]
	v_mfma_f32_16x16x32_bf16 v[38:41], v[18:21], v[42:45], 0
	v_mfma_f32_16x16x32_bf16 v[42:45], v[26:29], v[42:45], 0
	v_mfma_f32_16x16x32_bf16 v[38:41], v[22:25], v[46:49], v[38:41]
	v_mfma_f32_16x16x32_bf16 v[42:45], v[30:33], v[46:49], v[42:45]
	v_mfma_f32_16x16x32_bf16 v[46:49], v[18:21], v[50:53], 0
	v_mfma_f32_16x16x32_bf16 v[50:53], v[26:29], v[50:53], 0
	v_mfma_f32_16x16x32_bf16 v[46:49], v[22:25], v[54:57], v[46:49]
	v_mfma_f32_16x16x32_bf16 v[50:53], v[30:33], v[54:57], v[50:53]
	v_mfma_f32_16x16x32_bf16 v[54:57], v[18:21], v[58:61], 0
	v_mfma_f32_16x16x32_bf16 v[58:61], v[26:29], v[58:61], 0
	v_mfma_f32_16x16x32_bf16 v[54:57], v[22:25], v[62:65], v[54:57]
	v_mfma_f32_16x16x32_bf16 v[58:61], v[30:33], v[62:65], v[58:61]
	s_barrier
	s_add_i32 s72, s62, s33
	v_lshl_add_u64 v[204:205], s[48:49], 0, v[130:131]
	s_add_i32 s37, s72, 0x2000
	v_lshl_add_u64 v[140:141], v[204:205], 0, s[20:21]
	s_mov_b32 m0, s72
	v_lshl_add_u64 v[206:207], s[48:49], 0, v[132:133]
	s_add_u32 s80, s48, 0x10100
	ds_read_b128 v[62:65], v138 offset:16384
	ds_read_b128 v[102:105], v138 offset:17408
	ds_read_b128 v[106:109], v138 offset:18432
	ds_read_b128 v[110:113], v138 offset:19456
	ds_read_b128 v[114:117], v138 offset:20480
	ds_read_b128 v[118:121], v138 offset:21504
	ds_read_b128 v[122:125], v138 offset:22528
	ds_read_b128 v[126:129], v138 offset:23552
	global_load_lds_dwordx4 v[140:141], off
	v_lshl_add_u64 v[140:141], v[206:207], 0, s[20:21]
	s_mov_b32 m0, s37
	s_addc_u32 s81, s49, 0
	s_add_i32 s70, s63, s33
	global_load_lds_dwordx4 v[140:141], off
	v_lshl_add_u64 v[140:141], s[80:81], 0, v[130:131]
	s_mov_b32 m0, s70
	s_add_i32 s71, s70, 0x2000
	global_load_lds_dwordx4 v[140:141], off
	v_lshl_add_u64 v[140:141], s[80:81], 0, v[132:133]
	s_mov_b32 m0, s71
	v_lshl_add_u64 v[208:209], s[46:47], 0, v[130:131]
	global_load_lds_dwordx4 v[140:141], off
	v_lshl_add_u64 v[140:141], v[208:209], 0, s[20:21]
	s_mov_b32 m0, s45
	v_lshl_add_u64 v[210:211], s[46:47], 0, v[132:133]
	global_load_lds_dwordx4 v[140:141], off
	v_lshl_add_u64 v[140:141], v[210:211], 0, s[20:21]
	s_mov_b32 m0, s54
	s_nop 0
	global_load_lds_dwordx4 v[140:141], off
	s_waitcnt vmcnt(8)
	s_waitcnt lgkmcnt(0)
	s_barrier
; #define PG8_STAGE(bufoff, gbase, voff) do { _Pragma("unroll") for (int _i = 0; _i < 2; ++_i) \
;         __builtin_amdgcn_global_load_lds((const unsigned*)((const char*)(gbase) + (voff)[_i]), (PG8_LAS unsigned*)(lds + (bufoff) + ldsw + _i * 8192), 16, 0, 0); } while (0)
; #define PG8_LDA(dst, b, h) do { _Pragma("unroll") for (int m = 0; m < 4; ++m) _Pragma("unroll") for (int k = 0; k < 2; ++k) dst[m][k] = *(const PG8_LAS bf16x8*)(lds + PG8_SA(b, h) + aoff + m * 2048 + k * 1024); } while (0)
; #define PG8_LDB(dst, b, h) do { _Pragma("unroll") for (int n = 0; n < 2; ++n) _Pragma("unroll") for (int k = 0; k < 2; ++k) dst[n][k] = *(const PG8_LAS bf16x8*)(lds + PG8_SB(b, h) + boff + n * 2048 + k * 1024); } while (0)
; #define PG8_WAIT_V(n) asm volatile("s_waitcnt vmcnt(" #n ")" ::: "memory")
; #define PG8_WAIT_L(n) asm volatile("s_waitcnt lgkmcnt(" #n ")" ::: "memory")
; #define PG8_BAR __builtin_amdgcn_s_barrier()
; #define PG8_SCHED __builtin_amdgcn_sched_barrier(0)
; template <class Epi, class Sched, bool ALIGN_EPI = false, bool SP2 = false>
; __device__ __forceinline__ void gemm_phase(PG8_LAS unsigned char* lds, const Gemm g, const Sched& S, const Epi& E) {
;     ...
;             PG8_WAIT_V(8); PG8_WAIT_L(0); PG8_BAR; PG8_MMA(1, 0, At, B0); PG8_MMA(1, 1, At, B1); PG8_BAR; PG8_SCHED;
;             PG8_LDB(B0, 1, 0); PG8_LDB(B1, 1, 1); PG8_SCHED; PG8_LDA(At, 1, 0); PG8_STAGE(PG8_SA(0, 1), a2 + hstep, voffA);
;             PG8_WAIT_V(8); PG8_WAIT_L(0); PG8_BAR; PG8_MMA(0, 0, At, B0); PG8_MMA(0, 1, At, B1); PG8_BAR; PG8_SCHED;
	s_waitcnt lgkmcnt(0)
	v_mfma_f32_16x16x32_bf16 v[140:143], v[2:5], v[62:65], 0
	v_mfma_f32_16x16x32_bf16 v[148:151], v[2:5], v[106:109], 0
	v_mfma_f32_16x16x32_bf16 v[156:159], v[2:5], v[114:117], 0
	v_mfma_f32_16x16x32_bf16 v[2:5], v[2:5], v[122:125], 0
	v_mfma_f32_16x16x32_bf16 v[140:143], v[6:9], v[102:105], v[140:143]
	v_mfma_f32_16x16x32_bf16 v[148:151], v[6:9], v[110:113], v[148:151]
	v_mfma_f32_16x16x32_bf16 v[156:159], v[6:9], v[118:121], v[156:159]
	v_mfma_f32_16x16x32_bf16 v[2:5], v[6:9], v[126:129], v[2:5]
	v_mfma_f32_16x16x32_bf16 v[6:9], v[10:13], v[122:125], 0
	v_mfma_f32_16x16x32_bf16 v[144:147], v[10:13], v[62:65], 0
	v_mfma_f32_16x16x32_bf16 v[152:155], v[10:13], v[106:109], 0
	v_mfma_f32_16x16x32_bf16 v[160:163], v[10:13], v[114:117], 0
	v_mfma_f32_16x16x32_bf16 v[6:9], v[14:17], v[126:129], v[6:9]
	v_mfma_f32_16x16x32_bf16 v[144:147], v[14:17], v[102:105], v[144:147]
	v_mfma_f32_16x16x32_bf16 v[152:155], v[14:17], v[110:113], v[152:155]
	v_mfma_f32_16x16x32_bf16 v[160:163], v[14:17], v[118:121], v[160:163]
	v_mfma_f32_16x16x32_bf16 v[10:13], v[18:21], v[62:65], 0
	v_mfma_f32_16x16x32_bf16 v[14:17], v[26:29], v[62:65], 0
	v_mfma_f32_16x16x32_bf16 v[10:13], v[22:25], v[102:105], v[10:13]
	v_mfma_f32_16x16x32_bf16 v[14:17], v[30:33], v[102:105], v[14:17]
	v_mfma_f32_16x16x32_bf16 v[62:65], v[18:21], v[106:109], 0
	v_mfma_f32_16x16x32_bf16 v[102:105], v[26:29], v[106:109], 0
	v_mfma_f32_16x16x32_bf16 v[106:109], v[18:21], v[114:117], 0
	v_mfma_f32_16x16x32_bf16 v[18:21], v[18:21], v[122:125], 0
	v_mfma_f32_16x16x32_bf16 v[62:65], v[22:25], v[110:113], v[62:65]
	v_mfma_f32_16x16x32_bf16 v[102:105], v[30:33], v[110:113], v[102:105]
	v_mfma_f32_16x16x32_bf16 v[106:109], v[22:25], v[118:121], v[106:109]
	v_mfma_f32_16x16x32_bf16 v[110:113], v[26:29], v[114:117], 0
	v_mfma_f32_16x16x32_bf16 v[18:21], v[22:25], v[126:129], v[18:21]
	v_mfma_f32_16x16x32_bf16 v[22:25], v[26:29], v[122:125], 0
	v_mfma_f32_16x16x32_bf16 v[110:113], v[30:33], v[118:121], v[110:113]
	v_mfma_f32_16x16x32_bf16 v[22:25], v[30:33], v[126:129], v[22:25]
	s_barrier
	s_add_i32 s73, 0, 0x18000
	s_add_i32 s84, 0, 0x1c000
	v_add_u32_e32 v139, s73, v1
	v_add_u32_e32 v220, s84, v1
	ds_read_b128 v[26:29], v139
	ds_read_b128 v[30:33], v139 offset:1024
	ds_read_b128 v[114:117], v139 offset:2048
	ds_read_b128 v[118:121], v139 offset:3072
	ds_read_b128 v[122:125], v220
	ds_read_b128 v[126:129], v220 offset:1024
	ds_read_b128 v[164:167], v220 offset:2048
	ds_read_b128 v[168:171], v220 offset:3072
	s_add_u32 s80, s46, 0x10100
	s_addc_u32 s81, s47, 0
	s_mov_b32 m0, s55
	v_lshl_add_u64 v[212:213], s[80:81], 0, v[130:131]
	ds_read_b128 v[172:175], v138 offset:32768
	ds_read_b128 v[176:179], v138 offset:33792
	ds_read_b128 v[180:183], v138 offset:34816
	ds_read_b128 v[184:187], v138 offset:35840
	ds_read_b128 v[188:191], v138 offset:36864
	ds_read_b128 v[192:195], v138 offset:37888
	ds_read_b128 v[196:199], v138 offset:38912
	ds_read_b128 v[200:203], v138 offset:39936
	global_load_lds_dwordx4 v[212:213], off
	v_lshl_add_u64 v[212:213], s[80:81], 0, v[132:133]
	s_mov_b32 m0, s56
	s_nop 0
	global_load_lds_dwordx4 v[212:213], off
	s_waitcnt vmcnt(8)
	s_waitcnt lgkmcnt(0)
	s_barrier
	s_waitcnt lgkmcnt(0)
	v_mfma_f32_16x16x32_bf16 v[66:69], v[26:29], v[172:175], v[66:69]
	v_mfma_f32_16x16x32_bf16 v[70:73], v[114:117], v[172:175], v[70:73]
	v_mfma_f32_16x16x32_bf16 v[74:77], v[26:29], v[180:183], v[74:77]
	v_mfma_f32_16x16x32_bf16 v[78:81], v[114:117], v[180:183], v[78:81]
	v_mfma_f32_16x16x32_bf16 v[82:85], v[26:29], v[188:191], v[82:85]
	v_mfma_f32_16x16x32_bf16 v[86:89], v[114:117], v[188:191], v[86:89]
	v_mfma_f32_16x16x32_bf16 v[90:93], v[26:29], v[196:199], v[90:93]
	v_mfma_f32_16x16x32_bf16 v[94:97], v[114:117], v[196:199], v[94:97]
	v_mfma_f32_16x16x32_bf16 v[66:69], v[30:33], v[176:179], v[66:69]
	v_mfma_f32_16x16x32_bf16 v[70:73], v[118:121], v[176:179], v[70:73]
	v_mfma_f32_16x16x32_bf16 v[74:77], v[30:33], v[184:187], v[74:77]
	v_mfma_f32_16x16x32_bf16 v[78:81], v[118:121], v[184:187], v[78:81]
	v_mfma_f32_16x16x32_bf16 v[82:85], v[30:33], v[192:195], v[82:85]
	v_mfma_f32_16x16x32_bf16 v[86:89], v[118:121], v[192:195], v[86:89]
	v_mfma_f32_16x16x32_bf16 v[90:93], v[30:33], v[200:203], v[90:93]
	v_mfma_f32_16x16x32_bf16 v[94:97], v[118:121], v[200:203], v[94:97]
	v_mfma_f32_16x16x32_bf16 v[98:101], v[122:125], v[172:175], v[98:101]
	v_mfma_f32_16x16x32_bf16 v[34:37], v[164:167], v[172:175], v[34:37]
	v_mfma_f32_16x16x32_bf16 v[38:41], v[122:125], v[180:183], v[38:41]
	v_mfma_f32_16x16x32_bf16 v[42:45], v[164:167], v[180:183], v[42:45]
	v_mfma_f32_16x16x32_bf16 v[46:49], v[122:125], v[188:191], v[46:49]
	v_mfma_f32_16x16x32_bf16 v[50:53], v[164:167], v[188:191], v[50:53]
	v_mfma_f32_16x16x32_bf16 v[54:57], v[122:125], v[196:199], v[54:57]
	v_mfma_f32_16x16x32_bf16 v[58:61], v[164:167], v[196:199], v[58:61]
	v_mfma_f32_16x16x32_bf16 v[98:101], v[126:129], v[176:179], v[98:101]
	v_mfma_f32_16x16x32_bf16 v[34:37], v[168:171], v[176:179], v[34:37]
	v_mfma_f32_16x16x32_bf16 v[38:41], v[126:129], v[184:187], v[38:41]
	v_mfma_f32_16x16x32_bf16 v[42:45], v[168:171], v[184:187], v[42:45]
	v_mfma_f32_16x16x32_bf16 v[46:49], v[126:129], v[192:195], v[46:49]
	v_mfma_f32_16x16x32_bf16 v[50:53], v[168:171], v[192:195], v[50:53]
	v_mfma_f32_16x16x32_bf16 v[54:57], v[126:129], v[200:203], v[54:57]
	v_mfma_f32_16x16x32_bf16 v[58:61], v[168:171], v[200:203], v[58:61]
	s_barrier
; #define PG8_STAGE(bufoff, gbase, voff) do { _Pragma("unroll") for (int _i = 0; _i < 2; ++_i) \
;         __builtin_amdgcn_global_load_lds((const unsigned*)((const char*)(gbase) + (voff)[_i]), (PG8_LAS unsigned*)(lds + (bufoff) + ldsw + _i * 8192), 16, 0, 0); } while (0)
; #define PG8_LDA(dst, b, h) do { _Pragma("unroll") for (int m = 0; m < 4; ++m) _Pragma("unroll") for (int k = 0; k < 2; ++k) dst[m][k] = *(const PG8_LAS bf16x8*)(lds + PG8_SA(b, h) + aoff + m * 2048 + k * 1024); } while (0)
; #define PG8_LDB(dst, b, h) do { _Pragma("unroll") for (int n = 0; n < 2; ++n) _Pragma("unroll") for (int k = 0; k < 2; ++k) dst[n][k] = *(const PG8_LAS bf16x8*)(lds + PG8_SB(b, h) + boff + n * 2048 + k * 1024); } while (0)
; #define PG8_WAIT_V(n) asm volatile("s_waitcnt vmcnt(" #n ")" ::: "memory")
; #define PG8_WAIT_L(n) asm volatile("s_waitcnt lgkmcnt(" #n ")" ::: "memory")
; #define PG8_BAR __builtin_amdgcn_s_barrier()
; #define PG8_SCHED __builtin_amdgcn_sched_barrier(0)
; template <class Epi, class Sched, bool ALIGN_EPI = false, bool SP2 = false>
; __device__ __forceinline__ void gemm_phase(PG8_LAS unsigned char* lds, const Gemm g, const Sched& S, const Epi& E) {
;     ...
;             PG8_LDB(B0, 0, 0); PG8_LDB(B1, 0, 1); PG8_SCHED; PG8_LDA(At, 0, 0); PG8_STAGE(PG8_SA(1, 1), a1 + hstep, voffA);
;             PG8_WAIT_V(8); PG8_WAIT_L(0); PG8_BAR; PG8_MMA(0, 0, At, B0); PG8_MMA(0, 1, At, B1); PG8_BAR; PG8_SCHED;
;     ...
;             PG8_LDA(At, 1, 1); PG8_STAGE(PG8_SB(1, 0), b3, voffB); PG8_STAGE(PG8_SB(1, 1), b3 + hstep, voffB); PG8_STAGE(PG8_SA(1, 0), a3, voffA);
;             PG8_WAIT_V(8); PG8_WAIT_L(0); PG8_BAR; PG8_MMA(1, 0, At, B0); PG8_MMA(1, 1, At, B1); PG8_BAR; PG8_SCHED;
	s_add_i32 s80, s73, s33
	s_add_i32 s73, s80, 0x2000
	v_lshl_add_u64 v[204:205], v[204:205], 0, s[22:23]
	s_mov_b32 m0, s80
	s_add_u32 s82, s48, 0x10180
	ds_read_b128 v[172:175], v138 offset:49152
	ds_read_b128 v[176:179], v138 offset:50176
	ds_read_b128 v[180:183], v138 offset:51200
	ds_read_b128 v[184:187], v138 offset:52224
	ds_read_b128 v[188:191], v138 offset:53248
	ds_read_b128 v[192:195], v138 offset:54272
	ds_read_b128 v[196:199], v138 offset:55296
	ds_read_b128 v[200:203], v138 offset:56320
	global_load_lds_dwordx4 v[204:205], off
	v_lshl_add_u64 v[204:205], v[206:207], 0, s[22:23]
	s_mov_b32 m0, s73
	s_addc_u32 s83, s49, 0
	s_add_i32 s48, s84, s33
	global_load_lds_dwordx4 v[204:205], off
	v_lshl_add_u64 v[204:205], s[82:83], 0, v[130:131]
	s_mov_b32 m0, s48
	s_add_i32 s49, s48, 0x2000
	global_load_lds_dwordx4 v[204:205], off
	v_lshl_add_u64 v[204:205], s[82:83], 0, v[132:133]
	s_mov_b32 m0, s49
	s_nop 0
	global_load_lds_dwordx4 v[204:205], off
	v_lshl_add_u64 v[204:205], v[208:209], 0, s[22:23]
	s_mov_b32 m0, s57
	s_nop 0
	global_load_lds_dwordx4 v[204:205], off
	v_lshl_add_u64 v[204:205], v[210:211], 0, s[22:23]
	s_mov_b32 m0, s58
	s_nop 0
	global_load_lds_dwordx4 v[204:205], off
	s_waitcnt vmcnt(8)
	s_waitcnt lgkmcnt(0)
	s_barrier
	s_waitcnt lgkmcnt(0)
	v_mfma_f32_16x16x32_bf16 v[2:5], v[26:29], v[196:199], v[2:5]
	v_mfma_f32_16x16x32_bf16 v[6:9], v[114:117], v[196:199], v[6:9]
	v_mfma_f32_16x16x32_bf16 v[140:143], v[26:29], v[172:175], v[140:143]
	v_mfma_f32_16x16x32_bf16 v[144:147], v[114:117], v[172:175], v[144:147]
	v_mfma_f32_16x16x32_bf16 v[148:151], v[26:29], v[180:183], v[148:151]
	v_mfma_f32_16x16x32_bf16 v[152:155], v[114:117], v[180:183], v[152:155]
	v_mfma_f32_16x16x32_bf16 v[156:159], v[26:29], v[188:191], v[156:159]
	v_mfma_f32_16x16x32_bf16 v[160:163], v[114:117], v[188:191], v[160:163]
	v_mfma_f32_16x16x32_bf16 v[2:5], v[30:33], v[200:203], v[2:5]
	v_mfma_f32_16x16x32_bf16 v[6:9], v[118:121], v[200:203], v[6:9]
	v_mfma_f32_16x16x32_bf16 v[140:143], v[30:33], v[176:179], v[140:143]
	v_mfma_f32_16x16x32_bf16 v[144:147], v[118:121], v[176:179], v[144:147]
	v_mfma_f32_16x16x32_bf16 v[148:151], v[30:33], v[184:187], v[148:151]
	v_mfma_f32_16x16x32_bf16 v[152:155], v[118:121], v[184:187], v[152:155]
	v_mfma_f32_16x16x32_bf16 v[156:159], v[30:33], v[192:195], v[156:159]
	v_mfma_f32_16x16x32_bf16 v[160:163], v[118:121], v[192:195], v[160:163]
	v_mfma_f32_16x16x32_bf16 v[10:13], v[122:125], v[172:175], v[10:13]
	v_mfma_f32_16x16x32_bf16 v[14:17], v[164:167], v[172:175], v[14:17]
	v_mfma_f32_16x16x32_bf16 v[26:29], v[122:125], v[180:183], v[62:65]
	v_mfma_f32_16x16x32_bf16 v[30:33], v[164:167], v[180:183], v[102:105]
	v_mfma_f32_16x16x32_bf16 v[62:65], v[122:125], v[188:191], v[106:109]
	v_mfma_f32_16x16x32_bf16 v[102:105], v[164:167], v[188:191], v[110:113]
	v_mfma_f32_16x16x32_bf16 v[18:21], v[122:125], v[196:199], v[18:21]
	v_mfma_f32_16x16x32_bf16 v[22:25], v[164:167], v[196:199], v[22:25]
	v_mfma_f32_16x16x32_bf16 v[10:13], v[126:129], v[176:179], v[10:13]
	v_mfma_f32_16x16x32_bf16 v[14:17], v[168:171], v[176:179], v[14:17]
	v_mfma_f32_16x16x32_bf16 v[26:29], v[126:129], v[184:187], v[26:29]
	v_mfma_f32_16x16x32_bf16 v[30:33], v[168:171], v[184:187], v[30:33]
	v_mfma_f32_16x16x32_bf16 v[62:65], v[126:129], v[192:195], v[62:65]
	v_mfma_f32_16x16x32_bf16 v[102:105], v[168:171], v[192:195], v[102:105]
	v_mfma_f32_16x16x32_bf16 v[18:21], v[126:129], v[200:203], v[18:21]
	v_mfma_f32_16x16x32_bf16 v[22:25], v[168:171], v[200:203], v[22:25]
	s_barrier
	ds_read_b128 v[106:109], v136
	ds_read_b128 v[110:113], v136 offset:1024
	ds_read_b128 v[114:117], v136 offset:2048
	ds_read_b128 v[118:121], v136 offset:3072
	ds_read_b128 v[122:125], v137
	ds_read_b128 v[126:129], v137 offset:1024
	ds_read_b128 v[164:167], v137 offset:2048
	ds_read_b128 v[168:171], v137 offset:3072
	s_add_u32 s46, s46, 0x10180
	s_addc_u32 s47, s47, 0
	s_mov_b32 m0, s75
	v_lshl_add_u64 v[204:205], s[46:47], 0, v[130:131]
	ds_read_b128 v[172:175], v138
	ds_read_b128 v[176:179], v138 offset:1024
	ds_read_b128 v[180:183], v138 offset:2048
	ds_read_b128 v[184:187], v138 offset:3072
	ds_read_b128 v[188:191], v138 offset:4096
	ds_read_b128 v[192:195], v138 offset:5120
	ds_read_b128 v[196:199], v138 offset:6144
	ds_read_b128 v[200:203], v138 offset:7168
	global_load_lds_dwordx4 v[204:205], off
	v_lshl_add_u64 v[204:205], s[46:47], 0, v[132:133]
	s_mov_b32 m0, s35
	s_nop 0
	global_load_lds_dwordx4 v[204:205], off
	s_waitcnt vmcnt(8)
	s_waitcnt lgkmcnt(0)
	s_barrier
; #define PG8_STAGE(bufoff, gbase, voff) do { _Pragma("unroll") for (int _i = 0; _i < 2; ++_i) \
;         __builtin_amdgcn_global_load_lds((const unsigned*)((const char*)(gbase) + (voff)[_i]), (PG8_LAS unsigned*)(lds + (bufoff) + ldsw + _i * 8192), 16, 0, 0); } while (0)
; #define PG8_LDA(dst, b, h) do { _Pragma("unroll") for (int m = 0; m < 4; ++m) _Pragma("unroll") for (int k = 0; k < 2; ++k) dst[m][k] = *(const PG8_LAS bf16x8*)(lds + PG8_SA(b, h) + aoff + m * 2048 + k * 1024); } while (0)
; #define PG8_WAIT_V(n) asm volatile("s_waitcnt vmcnt(" #n ")" ::: "memory")
; #define PG8_WAIT_L(n) asm volatile("s_waitcnt lgkmcnt(" #n ")" ::: "memory")
; #define PG8_BAR __builtin_amdgcn_s_barrier()
; #define PG8_SCHED __builtin_amdgcn_sched_barrier(0)
; template <class Epi, class Sched, bool ALIGN_EPI = false, bool SP2 = false>
; __device__ __forceinline__ void gemm_phase(PG8_LAS unsigned char* lds, const Gemm g, const Sched& S, const Epi& E) {
;     ...
;             PG8_WAIT_V(8); PG8_WAIT_L(0); PG8_BAR; PG8_MMA(0, 0, At, B0); PG8_MMA(0, 1, At, B1); PG8_BAR; PG8_SCHED;
;             PG8_LDA(At, 0, 1); PG8_STAGE(PG8_SB(0, 0), b2, voffB); PG8_STAGE(PG8_SB(0, 1), b2 + hstep, voffB); PG8_STAGE(PG8_SA(0, 0), a2, voffA);
;             PG8_WAIT_V(8); PG8_WAIT_L(0); PG8_BAR; PG8_MMA(1, 0, At, B0); PG8_MMA(1, 1, At, B1); PG8_BAR; PG8_SCHED;
	s_waitcnt lgkmcnt(0)
	v_mfma_f32_16x16x32_bf16 v[66:69], v[106:109], v[172:175], v[66:69]
	v_mfma_f32_16x16x32_bf16 v[70:73], v[114:117], v[172:175], v[70:73]
	v_mfma_f32_16x16x32_bf16 v[74:77], v[106:109], v[180:183], v[74:77]
	v_mfma_f32_16x16x32_bf16 v[78:81], v[114:117], v[180:183], v[78:81]
	v_mfma_f32_16x16x32_bf16 v[82:85], v[106:109], v[188:191], v[82:85]
	v_mfma_f32_16x16x32_bf16 v[86:89], v[114:117], v[188:191], v[86:89]
	v_mfma_f32_16x16x32_bf16 v[90:93], v[106:109], v[196:199], v[90:93]
	v_mfma_f32_16x16x32_bf16 v[66:69], v[110:113], v[176:179], v[66:69]
	v_mfma_f32_16x16x32_bf16 v[70:73], v[118:121], v[176:179], v[70:73]
	v_mfma_f32_16x16x32_bf16 v[74:77], v[110:113], v[184:187], v[74:77]
	v_mfma_f32_16x16x32_bf16 v[78:81], v[118:121], v[184:187], v[78:81]
	v_mfma_f32_16x16x32_bf16 v[82:85], v[110:113], v[192:195], v[82:85]
	v_mfma_f32_16x16x32_bf16 v[86:89], v[118:121], v[192:195], v[86:89]
	v_mfma_f32_16x16x32_bf16 v[90:93], v[110:113], v[200:203], v[90:93]
	v_mfma_f32_16x16x32_bf16 v[94:97], v[114:117], v[196:199], v[94:97]
	v_mfma_f32_16x16x32_bf16 v[204:207], v[118:121], v[200:203], v[94:97]
	v_mfma_f32_16x16x32_bf16 v[94:97], v[122:125], v[172:175], v[98:101]
	v_mfma_f32_16x16x32_bf16 v[34:37], v[164:167], v[172:175], v[34:37]
	v_mfma_f32_16x16x32_bf16 v[38:41], v[122:125], v[180:183], v[38:41]
	v_mfma_f32_16x16x32_bf16 v[42:45], v[164:167], v[180:183], v[42:45]
	v_mfma_f32_16x16x32_bf16 v[46:49], v[122:125], v[188:191], v[46:49]
	v_mfma_f32_16x16x32_bf16 v[50:53], v[164:167], v[188:191], v[50:53]
	v_mfma_f32_16x16x32_bf16 v[54:57], v[122:125], v[196:199], v[54:57]
	v_mfma_f32_16x16x32_bf16 v[98:101], v[126:129], v[176:179], v[94:97]
	v_mfma_f32_16x16x32_bf16 v[34:37], v[168:171], v[176:179], v[34:37]
	v_mfma_f32_16x16x32_bf16 v[38:41], v[126:129], v[184:187], v[38:41]
	v_mfma_f32_16x16x32_bf16 v[42:45], v[168:171], v[184:187], v[42:45]
	v_mfma_f32_16x16x32_bf16 v[46:49], v[126:129], v[192:195], v[46:49]
	v_mfma_f32_16x16x32_bf16 v[50:53], v[168:171], v[192:195], v[50:53]
	v_mfma_f32_16x16x32_bf16 v[172:175], v[126:129], v[200:203], v[54:57]
	v_mfma_f32_16x16x32_bf16 v[54:57], v[164:167], v[196:199], v[58:61]
	v_mfma_f32_16x16x32_bf16 v[176:179], v[168:171], v[200:203], v[54:57]
	s_barrier
	s_mov_b32 m0, s72
	v_lshl_add_u64 v[244:245], s[50:51], 0, v[130:131]
	s_add_u32 s46, s50, 0x10000
	s_nop 1
	ds_read_b128 v[54:57], v138 offset:16384
	ds_read_b128 v[58:61], v138 offset:17408
	ds_read_b128 v[94:97], v138 offset:18432
	ds_read_b128 v[180:183], v138 offset:19456
	ds_read_b128 v[184:187], v138 offset:20480
	ds_read_b128 v[188:191], v138 offset:21504
	ds_read_b128 v[192:195], v138 offset:22528
	ds_read_b128 v[196:199], v138 offset:23552
	global_load_lds_dwordx4 v[244:245], off
	v_lshl_add_u64 v[246:247], s[50:51], 0, v[132:133]
	s_mov_b32 m0, s37
	s_addc_u32 s47, s51, 0
	global_load_lds_dwordx4 v[246:247], off
	v_lshl_add_u64 v[200:201], s[46:47], 0, v[130:131]
	s_mov_b32 m0, s70
	v_lshl_add_u64 v[248:249], s[52:53], 0, v[130:131]
	global_load_lds_dwordx4 v[200:201], off
	v_lshl_add_u64 v[200:201], s[46:47], 0, v[132:133]
	s_mov_b32 m0, s71
	v_lshl_add_u64 v[250:251], s[52:53], 0, v[132:133]
	global_load_lds_dwordx4 v[200:201], off
	s_mov_b32 m0, s45
	s_nop 0
	global_load_lds_dwordx4 v[248:249], off
	s_mov_b32 m0, s54
	s_nop 0
	global_load_lds_dwordx4 v[250:251], off
	s_waitcnt vmcnt(8)
	s_waitcnt lgkmcnt(0)
	s_barrier
	s_waitcnt lgkmcnt(0)
	v_mfma_f32_16x16x32_bf16 v[2:5], v[106:109], v[192:195], v[2:5]
	v_mfma_f32_16x16x32_bf16 v[6:9], v[114:117], v[192:195], v[6:9]
	v_mfma_f32_16x16x32_bf16 v[140:143], v[106:109], v[54:57], v[140:143]
	v_mfma_f32_16x16x32_bf16 v[144:147], v[114:117], v[54:57], v[144:147]
	v_mfma_f32_16x16x32_bf16 v[148:151], v[106:109], v[94:97], v[148:151]
	v_mfma_f32_16x16x32_bf16 v[152:155], v[114:117], v[94:97], v[152:155]
	v_mfma_f32_16x16x32_bf16 v[156:159], v[106:109], v[184:187], v[156:159]
	v_mfma_f32_16x16x32_bf16 v[160:163], v[114:117], v[184:187], v[160:163]
	v_mfma_f32_16x16x32_bf16 v[2:5], v[110:113], v[196:199], v[2:5]
	v_mfma_f32_16x16x32_bf16 v[6:9], v[118:121], v[196:199], v[6:9]
	v_mfma_f32_16x16x32_bf16 v[140:143], v[110:113], v[58:61], v[140:143]
	v_mfma_f32_16x16x32_bf16 v[144:147], v[118:121], v[58:61], v[144:147]
	v_mfma_f32_16x16x32_bf16 v[148:151], v[110:113], v[180:183], v[148:151]
	v_mfma_f32_16x16x32_bf16 v[152:155], v[118:121], v[180:183], v[152:155]
	v_mfma_f32_16x16x32_bf16 v[156:159], v[110:113], v[188:191], v[156:159]
	v_mfma_f32_16x16x32_bf16 v[160:163], v[118:121], v[188:191], v[160:163]
	v_mfma_f32_16x16x32_bf16 v[14:17], v[164:167], v[54:57], v[14:17]
	v_mfma_f32_16x16x32_bf16 v[200:203], v[168:171], v[58:61], v[14:17]
	v_mfma_f32_16x16x32_bf16 v[14:17], v[122:125], v[94:97], v[26:29]
	v_mfma_f32_16x16x32_bf16 v[26:29], v[126:129], v[180:183], v[14:17]
	v_mfma_f32_16x16x32_bf16 v[14:17], v[164:167], v[94:97], v[30:33]
	v_mfma_f32_16x16x32_bf16 v[180:183], v[168:171], v[180:183], v[14:17]
	v_mfma_f32_16x16x32_bf16 v[14:17], v[122:125], v[184:187], v[62:65]
	v_mfma_f32_16x16x32_bf16 v[208:211], v[126:129], v[188:191], v[14:17]
	v_mfma_f32_16x16x32_bf16 v[14:17], v[164:167], v[184:187], v[102:105]
	v_mfma_f32_16x16x32_bf16 v[10:13], v[122:125], v[54:57], v[10:13]
	v_mfma_f32_16x16x32_bf16 v[184:187], v[168:171], v[188:191], v[14:17]
	v_mfma_f32_16x16x32_bf16 v[14:17], v[122:125], v[192:195], v[18:21]
	v_mfma_f32_16x16x32_bf16 v[10:13], v[126:129], v[58:61], v[10:13]
	v_mfma_f32_16x16x32_bf16 v[188:191], v[126:129], v[196:199], v[14:17]
	v_mfma_f32_16x16x32_bf16 v[14:17], v[164:167], v[192:195], v[22:25]
	v_mfma_f32_16x16x32_bf16 v[164:167], v[168:171], v[196:199], v[14:17]
	s_barrier
; #define PG8_STAGE(bufoff, gbase, voff) do { _Pragma("unroll") for (int _i = 0; _i < 2; ++_i) \
;         __builtin_amdgcn_global_load_lds((const unsigned*)((const char*)(gbase) + (voff)[_i]), (PG8_LAS unsigned*)(lds + (bufoff) + ldsw + _i * 8192), 16, 0, 0); } while (0)
; #define PG8_LDA(dst, b, h) do { _Pragma("unroll") for (int m = 0; m < 4; ++m) _Pragma("unroll") for (int k = 0; k < 2; ++k) dst[m][k] = *(const PG8_LAS bf16x8*)(lds + PG8_SA(b, h) + aoff + m * 2048 + k * 1024); } while (0)
; #define PG8_LDB(dst, b, h) do { _Pragma("unroll") for (int n = 0; n < 2; ++n) _Pragma("unroll") for (int k = 0; k < 2; ++k) dst[n][k] = *(const PG8_LAS bf16x8*)(lds + PG8_SB(b, h) + boff + n * 2048 + k * 1024); } while (0)
; #define PG8_WAIT_V(n) asm volatile("s_waitcnt vmcnt(" #n ")" ::: "memory")
; #define PG8_WAIT_L(n) asm volatile("s_waitcnt lgkmcnt(" #n ")" ::: "memory")
; #define PG8_BAR __builtin_amdgcn_s_barrier()
; #define PG8_SCHED __builtin_amdgcn_sched_barrier(0)
; template <class Epi, class Sched, bool ALIGN_EPI = false, bool SP2 = false>
; __device__ __forceinline__ void gemm_phase(PG8_LAS unsigned char* lds, const Gemm g, const Sched& S, const Epi& E) {
;     ...
;             PG8_LDB(B0, 1, 0); PG8_LDB(B1, 1, 1); PG8_SCHED; PG8_LDA(At, 1, 0); PG8_STAGE(PG8_SA(0, 1), a2 + hstep, voffA);
;             PG8_WAIT_V(8); PG8_WAIT_L(0); PG8_BAR; PG8_MMA(0, 0, At, B0); PG8_MMA(0, 1, At, B1); PG8_BAR; PG8_SCHED;
;             PG8_LDA(At, 1, 1); PG8_STAGE(PG8_SB(1, 0), b3, voffB); PG8_STAGE(PG8_SB(1, 1), b3 + hstep, voffB); PG8_STAGE(PG8_SA(1, 0), a3, voffA);
;             PG8_WAIT_V(8); PG8_WAIT_L(0); PG8_BAR; PG8_MMA(1, 0, At, B0); PG8_MMA(1, 1, At, B1); PG8_BAR; PG8_SCHED;
;     ...
;         if (!has_next) break;
	s_nop 4
	ds_read_b128 v[14:17], v139
	ds_read_b128 v[18:21], v139 offset:1024
	ds_read_b128 v[168:171], v139 offset:2048
	ds_read_b128 v[192:195], v139 offset:3072
	ds_read_b128 v[196:199], v220
	ds_read_b128 v[212:215], v220 offset:1024
	ds_read_b128 v[216:219], v220 offset:2048
	ds_read_b128 v[220:223], v220 offset:3072
	s_add_u32 s46, s52, 0x10000
	s_addc_u32 s47, s53, 0
	s_mov_b32 m0, s55
	v_lshl_add_u64 v[54:55], s[46:47], 0, v[130:131]
	ds_read_b128 v[22:25], v138 offset:32768
	ds_read_b128 v[30:33], v138 offset:33792
	ds_read_b128 v[58:61], v138 offset:34816
	ds_read_b128 v[224:227], v138 offset:35840
	ds_read_b128 v[228:231], v138 offset:36864
	ds_read_b128 v[232:235], v138 offset:37888
	ds_read_b128 v[236:239], v138 offset:38912
	ds_read_b128 v[240:243], v138 offset:39936
	global_load_lds_dwordx4 v[54:55], off
	v_lshl_add_u64 v[54:55], s[46:47], 0, v[132:133]
	s_mov_b32 m0, s56
	s_nop 0
	global_load_lds_dwordx4 v[54:55], off
	s_waitcnt vmcnt(8)
	s_waitcnt lgkmcnt(0)
	s_barrier
	s_waitcnt lgkmcnt(0)
	v_mfma_f32_16x16x32_bf16 v[54:57], v[14:17], v[22:25], v[66:69]
	v_mfma_f32_16x16x32_bf16 v[126:129], v[18:21], v[30:33], v[54:57]
	v_mfma_f32_16x16x32_bf16 v[54:57], v[168:171], v[22:25], v[70:73]
	v_mfma_f32_16x16x32_bf16 v[118:121], v[192:195], v[30:33], v[54:57]
	v_mfma_f32_16x16x32_bf16 v[54:57], v[14:17], v[58:61], v[74:77]
	v_mfma_f32_16x16x32_bf16 v[110:113], v[18:21], v[224:227], v[54:57]
	v_mfma_f32_16x16x32_bf16 v[54:57], v[168:171], v[58:61], v[78:81]
	v_mfma_f32_16x16x32_bf16 v[102:105], v[192:195], v[224:227], v[54:57]
	v_mfma_f32_16x16x32_bf16 v[54:57], v[14:17], v[228:231], v[82:85]
	v_mfma_f32_16x16x32_bf16 v[94:97], v[18:21], v[232:235], v[54:57]
	v_mfma_f32_16x16x32_bf16 v[54:57], v[168:171], v[228:231], v[86:89]
	v_mfma_f32_16x16x32_bf16 v[86:89], v[192:195], v[232:235], v[54:57]
	v_mfma_f32_16x16x32_bf16 v[54:57], v[14:17], v[236:239], v[90:93]
	v_mfma_f32_16x16x32_bf16 v[62:65], v[18:21], v[240:243], v[54:57]
	v_mfma_f32_16x16x32_bf16 v[54:57], v[168:171], v[236:239], v[204:207]
	v_mfma_f32_16x16x32_bf16 v[54:57], v[192:195], v[240:243], v[54:57]
	v_mfma_f32_16x16x32_bf16 v[66:69], v[196:199], v[22:25], v[98:101]
	v_mfma_f32_16x16x32_bf16 v[22:25], v[216:219], v[22:25], v[34:37]
	v_mfma_f32_16x16x32_bf16 v[114:117], v[220:223], v[30:33], v[22:25]
	v_mfma_f32_16x16x32_bf16 v[22:25], v[196:199], v[58:61], v[38:41]
	v_mfma_f32_16x16x32_bf16 v[106:109], v[212:215], v[224:227], v[22:25]
	v_mfma_f32_16x16x32_bf16 v[22:25], v[216:219], v[58:61], v[42:45]
	v_mfma_f32_16x16x32_bf16 v[98:101], v[220:223], v[224:227], v[22:25]
	v_mfma_f32_16x16x32_bf16 v[22:25], v[196:199], v[228:231], v[46:49]
	v_mfma_f32_16x16x32_bf16 v[90:93], v[212:215], v[232:235], v[22:25]
	v_mfma_f32_16x16x32_bf16 v[22:25], v[216:219], v[228:231], v[50:53]
	v_mfma_f32_16x16x32_bf16 v[82:85], v[220:223], v[232:235], v[22:25]
	v_mfma_f32_16x16x32_bf16 v[22:25], v[196:199], v[236:239], v[172:175]
	v_mfma_f32_16x16x32_bf16 v[58:61], v[212:215], v[240:243], v[22:25]
	v_mfma_f32_16x16x32_bf16 v[22:25], v[216:219], v[236:239], v[176:179]
	v_mfma_f32_16x16x32_bf16 v[122:125], v[212:215], v[30:33], v[66:69]
	v_mfma_f32_16x16x32_bf16 v[50:53], v[220:223], v[240:243], v[22:25]
	s_barrier
	s_mov_b32 m0, s80
	s_nop 2
	v_lshl_add_u64 v[22:23], v[244:245], 0, s[14:15]
	s_add_u32 s46, s50, 0x10080
	ds_read_b128 v[34:37], v138 offset:49152
	ds_read_b128 v[42:45], v138 offset:50176
	ds_read_b128 v[172:175], v138 offset:51200
	ds_read_b128 v[176:179], v138 offset:52224
	ds_read_b128 v[204:207], v138 offset:53248
	ds_read_b128 v[224:227], v138 offset:54272
	ds_read_b128 v[228:231], v138 offset:55296
	ds_read_b128 v[232:235], v138 offset:56320
	global_load_lds_dwordx4 v[22:23], off
	v_lshl_add_u64 v[22:23], v[246:247], 0, s[14:15]
	s_mov_b32 m0, s73
	s_addc_u32 s47, s51, 0
	global_load_lds_dwordx4 v[22:23], off
	v_lshl_add_u64 v[22:23], s[46:47], 0, v[130:131]
	s_mov_b32 m0, s48
	s_nop 0
	global_load_lds_dwordx4 v[22:23], off
	v_lshl_add_u64 v[22:23], s[46:47], 0, v[132:133]
	s_mov_b32 m0, s49
	s_nop 0
	global_load_lds_dwordx4 v[22:23], off
	v_lshl_add_u64 v[22:23], v[248:249], 0, s[14:15]
	s_mov_b32 m0, s57
	s_nop 0
	global_load_lds_dwordx4 v[22:23], off
	v_lshl_add_u64 v[22:23], v[250:251], 0, s[14:15]
	s_mov_b32 m0, s58
	s_nop 0
	global_load_lds_dwordx4 v[22:23], off
	s_waitcnt vmcnt(8)
	s_waitcnt lgkmcnt(0)
	s_barrier
	s_waitcnt lgkmcnt(0)
	v_mfma_f32_16x16x32_bf16 v[22:25], v[14:17], v[34:37], v[140:143]
	v_mfma_f32_16x16x32_bf16 v[78:81], v[18:21], v[42:45], v[22:25]
	v_mfma_f32_16x16x32_bf16 v[22:25], v[168:171], v[34:37], v[144:147]
	v_mfma_f32_16x16x32_bf16 v[70:73], v[192:195], v[42:45], v[22:25]
	v_mfma_f32_16x16x32_bf16 v[22:25], v[14:17], v[172:175], v[148:151]
	v_mfma_f32_16x16x32_bf16 v[46:49], v[18:21], v[176:179], v[22:25]
	v_mfma_f32_16x16x32_bf16 v[22:25], v[168:171], v[172:175], v[152:155]
	v_mfma_f32_16x16x32_bf16 v[38:41], v[192:195], v[176:179], v[22:25]
	v_mfma_f32_16x16x32_bf16 v[22:25], v[14:17], v[204:207], v[156:159]
	v_mfma_f32_16x16x32_bf16 v[2:5], v[14:17], v[228:231], v[2:5]
	v_mfma_f32_16x16x32_bf16 v[30:33], v[18:21], v[224:227], v[22:25]
	v_mfma_f32_16x16x32_bf16 v[22:25], v[168:171], v[204:207], v[160:163]
	v_mfma_f32_16x16x32_bf16 v[14:17], v[18:21], v[232:235], v[2:5]
	v_mfma_f32_16x16x32_bf16 v[2:5], v[168:171], v[228:231], v[6:9]
	v_mfma_f32_16x16x32_bf16 v[22:25], v[192:195], v[224:227], v[22:25]
	v_mfma_f32_16x16x32_bf16 v[6:9], v[192:195], v[232:235], v[2:5]
	v_mfma_f32_16x16x32_bf16 v[2:5], v[196:199], v[34:37], v[10:13]
	v_mfma_f32_16x16x32_bf16 v[74:77], v[212:215], v[42:45], v[2:5]
	v_mfma_f32_16x16x32_bf16 v[2:5], v[216:219], v[34:37], v[200:203]
	v_mfma_f32_16x16x32_bf16 v[66:69], v[220:223], v[42:45], v[2:5]
	v_mfma_f32_16x16x32_bf16 v[2:5], v[196:199], v[172:175], v[26:29]
	v_mfma_f32_16x16x32_bf16 v[42:45], v[212:215], v[176:179], v[2:5]
	v_mfma_f32_16x16x32_bf16 v[2:5], v[216:219], v[172:175], v[180:183]
	v_mfma_f32_16x16x32_bf16 v[34:37], v[220:223], v[176:179], v[2:5]
	v_mfma_f32_16x16x32_bf16 v[2:5], v[196:199], v[204:207], v[208:211]
	v_mfma_f32_16x16x32_bf16 v[26:29], v[212:215], v[224:227], v[2:5]
	v_mfma_f32_16x16x32_bf16 v[2:5], v[216:219], v[204:207], v[184:187]
	v_mfma_f32_16x16x32_bf16 v[18:21], v[220:223], v[224:227], v[2:5]
	v_mfma_f32_16x16x32_bf16 v[2:5], v[196:199], v[228:231], v[188:191]
	v_mfma_f32_16x16x32_bf16 v[10:13], v[212:215], v[232:235], v[2:5]
	v_mfma_f32_16x16x32_bf16 v[2:5], v[216:219], v[228:231], v[164:167]
	v_mfma_f32_16x16x32_bf16 v[2:5], v[220:223], v[232:235], v[2:5]
	s_barrier
	s_andn2_b64 vcc, exec, s[18:19]
	s_cbranch_vccnz .LBB0_437
	s_barrier

; #define PG8_STAGE(bufoff, gbase, voff) do { _Pragma("unroll") for (int _i = 0; _i < 2; ++_i) \
;         __builtin_amdgcn_global_load_lds((const unsigned*)((const char*)(gbase) + (voff)[_i]), (PG8_LAS unsigned*)(lds + (bufoff) + ldsw + _i * 8192), 16, 0, 0); } while (0)
; #define PG8_LDA(dst, b, h) do { _Pragma("unroll") for (int m = 0; m < 4; ++m) _Pragma("unroll") for (int k = 0; k < 2; ++k) dst[m][k] = *(const PG8_LAS bf16x8*)(lds + PG8_SA(b, h) + aoff + m * 2048 + k * 1024); } while (0)
; #define PG8_LDB(dst, b, h) do { _Pragma("unroll") for (int n = 0; n < 2; ++n) _Pragma("unroll") for (int k = 0; k < 2; ++k) dst[n][k] = *(const PG8_LAS bf16x8*)(lds + PG8_SB(b, h) + boff + n * 2048 + k * 1024); } while (0)
; #define PG8_WAIT_V(n) asm volatile("s_waitcnt vmcnt(" #n ")" ::: "memory")
; #define PG8_WAIT_L(n) asm volatile("s_waitcnt lgkmcnt(" #n ")" ::: "memory")
; #define PG8_BAR __builtin_amdgcn_s_barrier()
; #define PG8_SCHED __builtin_amdgcn_sched_barrier(0)
; template <class Epi, class Sched, bool ALIGN_EPI = false, bool SP2 = false>
; __device__ __forceinline__ void gemm_phase(PG8_LAS unsigned char* lds, const Gemm g, const Sched& S, const Epi& E) {
;     ...
;             PG8_LDB(B0, 0, 0); PG8_LDB(B1, 0, 1); PG8_SCHED; PG8_LDA(At, 0, 0); PG8_STAGE(PG8_SA(1, 1), a1 + hstep, voffA);
;             PG8_WAIT_V(8); PG8_WAIT_L(0); PG8_BAR; PG8_MMA(0, 0, At, B0); PG8_MMA(0, 1, At, B1); PG8_BAR; PG8_SCHED;
;             PG8_LDA(At, 0, 1); PG8_STAGE(PG8_SB(0, 0), b2, voffB); PG8_STAGE(PG8_SB(0, 1), b2 + hstep, voffB); PG8_STAGE(PG8_SA(0, 0), a2, voffA);
;             PG8_WAIT_V(8); PG8_WAIT_L(0); PG8_BAR; PG8_MMA(1, 0, At, B0); PG8_MMA(1, 1, At, B1); PG8_BAR; PG8_SCHED;
.LBB0_1132:
	v_add_u32_e32 v3, s69, v172
	ds_read_b128 v[168:171], v3
	ds_read_b128 v[186:189], v3 offset:1024
	ds_read_b128 v[190:193], v3 offset:2048
	ds_read_b128 v[194:197], v3 offset:3072
	v_add_u32_e32 v3, s70, v172
	s_add_u32 s10, s52, s54
	ds_read_b128 v[198:201], v3
	ds_read_b128 v[202:205], v3 offset:1024
	ds_read_b128 v[206:209], v3 offset:2048
	ds_read_b128 v[210:213], v3 offset:3072
	s_addc_u32 s11, s53, s55
	s_add_u32 s10, s10, 0x100
	s_addc_u32 s11, s11, 0
	s_add_u32 s14, s43, s54
	s_addc_u32 s15, s45, s55
	s_cmpk_eq_i32 s54, 0x1f00
	s_cselect_b32 s13, s1, s11
	s_cselect_b32 s12, s4, s10
	s_cselect_b32 s11, s5, s15
	s_cselect_b32 s10, s33, s14
	v_lshl_add_u64 v[4:5], v[164:165], 0, s[54:55]
	s_add_i32 m0, s51, 0xc000
	ds_read_b128 v[214:217], v182
	ds_read_b128 v[218:221], v182 offset:1024
	ds_read_b128 v[222:225], v182 offset:2048
	ds_read_b128 v[226:229], v182 offset:3072
	ds_read_b128 v[230:233], v182 offset:4096
	ds_read_b128 v[234:237], v182 offset:5120
	ds_read_b128 v[238:241], v182 offset:6144
	ds_read_b128 v[242:245], v182 offset:7168
	global_load_lds_dwordx4 v[4:5], off
	v_lshl_add_u64 v[4:5], v[166:167], 0, s[54:55]
	s_add_i32 m0, s51, 0xe000
	s_nop 0
	global_load_lds_dwordx4 v[4:5], off
	s_waitcnt vmcnt(8)
	s_waitcnt lgkmcnt(0)
	s_barrier
	s_waitcnt lgkmcnt(0)
	v_mfma_f32_16x16x32_bf16 v[130:133], v[168:171], v[214:217], v[130:133]
	v_mfma_f32_16x16x32_bf16 v[126:129], v[190:193], v[214:217], v[126:129]
	v_mfma_f32_16x16x32_bf16 v[114:117], v[168:171], v[222:225], v[114:117]
	v_mfma_f32_16x16x32_bf16 v[110:113], v[190:193], v[222:225], v[110:113]
	v_mfma_f32_16x16x32_bf16 v[98:101], v[168:171], v[230:233], v[98:101]
	v_mfma_f32_16x16x32_bf16 v[94:97], v[190:193], v[230:233], v[94:97]
	v_mfma_f32_16x16x32_bf16 v[82:85], v[168:171], v[238:241], v[82:85]
	v_mfma_f32_16x16x32_bf16 v[78:81], v[190:193], v[238:241], v[78:81]
	v_mfma_f32_16x16x32_bf16 v[130:133], v[186:189], v[218:221], v[130:133]
	v_mfma_f32_16x16x32_bf16 v[126:129], v[194:197], v[218:221], v[126:129]
	v_mfma_f32_16x16x32_bf16 v[114:117], v[186:189], v[226:229], v[114:117]
	v_mfma_f32_16x16x32_bf16 v[110:113], v[194:197], v[226:229], v[110:113]
	v_mfma_f32_16x16x32_bf16 v[98:101], v[186:189], v[234:237], v[98:101]
	v_mfma_f32_16x16x32_bf16 v[94:97], v[194:197], v[234:237], v[94:97]
	v_mfma_f32_16x16x32_bf16 v[82:85], v[186:189], v[242:245], v[82:85]
	v_mfma_f32_16x16x32_bf16 v[78:81], v[194:197], v[242:245], v[78:81]
	v_mfma_f32_16x16x32_bf16 v[122:125], v[198:201], v[214:217], v[122:125]
	v_mfma_f32_16x16x32_bf16 v[118:121], v[206:209], v[214:217], v[118:121]
	v_mfma_f32_16x16x32_bf16 v[106:109], v[198:201], v[222:225], v[106:109]
	v_mfma_f32_16x16x32_bf16 v[102:105], v[206:209], v[222:225], v[102:105]
	v_mfma_f32_16x16x32_bf16 v[90:93], v[198:201], v[230:233], v[90:93]
	v_mfma_f32_16x16x32_bf16 v[86:89], v[206:209], v[230:233], v[86:89]
	v_mfma_f32_16x16x32_bf16 v[74:77], v[198:201], v[238:241], v[74:77]
	v_mfma_f32_16x16x32_bf16 v[70:73], v[206:209], v[238:241], v[70:73]
	v_mfma_f32_16x16x32_bf16 v[122:125], v[202:205], v[218:221], v[122:125]
	v_mfma_f32_16x16x32_bf16 v[118:121], v[210:213], v[218:221], v[118:121]
	v_mfma_f32_16x16x32_bf16 v[106:109], v[202:205], v[226:229], v[106:109]
	v_mfma_f32_16x16x32_bf16 v[102:105], v[210:213], v[226:229], v[102:105]
	v_mfma_f32_16x16x32_bf16 v[90:93], v[202:205], v[234:237], v[90:93]
	v_mfma_f32_16x16x32_bf16 v[86:89], v[210:213], v[234:237], v[86:89]
	v_mfma_f32_16x16x32_bf16 v[74:77], v[202:205], v[242:245], v[74:77]
	v_mfma_f32_16x16x32_bf16 v[70:73], v[210:213], v[242:245], v[70:73]
	s_barrier
	s_add_i32 s14, s69, s59
	v_lshl_add_u64 v[246:247], s[10:11], 0, v[150:151]
	s_mov_b32 m0, s14
	ds_read_b128 v[214:217], v182 offset:16384
	ds_read_b128 v[218:221], v182 offset:17408
	ds_read_b128 v[222:225], v182 offset:18432
	ds_read_b128 v[226:229], v182 offset:19456
	ds_read_b128 v[230:233], v182 offset:20480
	ds_read_b128 v[234:237], v182 offset:21504
	ds_read_b128 v[238:241], v182 offset:22528
	ds_read_b128 v[242:245], v182 offset:23552
	global_load_lds_dwordx4 v[246:247], off
	s_add_i32 m0, s14, 0x2000
	s_add_u32 s14, s10, 0x100000
	v_lshl_add_u64 v[248:249], s[10:11], 0, v[152:153]
	s_addc_u32 s15, s11, 0
	s_add_i32 s16, s70, s59
	global_load_lds_dwordx4 v[248:249], off
	v_lshl_add_u64 v[4:5], s[14:15], 0, v[150:151]
	s_mov_b32 m0, s16
	v_lshl_add_u64 v[250:251], s[12:13], 0, v[150:151]
	global_load_lds_dwordx4 v[4:5], off
	v_lshl_add_u64 v[4:5], s[14:15], 0, v[152:153]
	s_add_i32 m0, s16, 0x2000
	v_lshl_add_u64 v[252:253], s[12:13], 0, v[152:153]
	global_load_lds_dwordx4 v[4:5], off
	s_mov_b32 m0, s51
	s_nop 0
	global_load_lds_dwordx4 v[250:251], off
	s_mov_b32 m0, s60
	s_nop 0
	global_load_lds_dwordx4 v[252:253], off
	s_waitcnt vmcnt(8)
	s_waitcnt lgkmcnt(0)
	s_barrier
; #define PG8_STAGE(bufoff, gbase, voff) do { _Pragma("unroll") for (int _i = 0; _i < 2; ++_i) \
;         __builtin_amdgcn_global_load_lds((const unsigned*)((const char*)(gbase) + (voff)[_i]), (PG8_LAS unsigned*)(lds + (bufoff) + ldsw + _i * 8192), 16, 0, 0); } while (0)
; #define PG8_LDA(dst, b, h) do { _Pragma("unroll") for (int m = 0; m < 4; ++m) _Pragma("unroll") for (int k = 0; k < 2; ++k) dst[m][k] = *(const PG8_LAS bf16x8*)(lds + PG8_SA(b, h) + aoff + m * 2048 + k * 1024); } while (0)
; #define PG8_LDB(dst, b, h) do { _Pragma("unroll") for (int n = 0; n < 2; ++n) _Pragma("unroll") for (int k = 0; k < 2; ++k) dst[n][k] = *(const PG8_LAS bf16x8*)(lds + PG8_SB(b, h) + boff + n * 2048 + k * 1024); } while (0)
; #define PG8_WAIT_V(n) asm volatile("s_waitcnt vmcnt(" #n ")" ::: "memory")
; #define PG8_WAIT_L(n) asm volatile("s_waitcnt lgkmcnt(" #n ")" ::: "memory")
; #define PG8_BAR __builtin_amdgcn_s_barrier()
; #define PG8_SCHED __builtin_amdgcn_sched_barrier(0)
; template <class Epi, class Sched, bool ALIGN_EPI = false, bool SP2 = false>
; __device__ __forceinline__ void gemm_phase(PG8_LAS unsigned char* lds, const Gemm g, const Sched& S, const Epi& E) {
;     ...
;             PG8_WAIT_V(8); PG8_WAIT_L(0); PG8_BAR; PG8_MMA(1, 0, At, B0); PG8_MMA(1, 1, At, B1); PG8_BAR; PG8_SCHED;
;             PG8_LDB(B0, 1, 0); PG8_LDB(B1, 1, 1); PG8_SCHED; PG8_LDA(At, 1, 0); PG8_STAGE(PG8_SA(0, 1), a2 + hstep, voffA);
;             PG8_WAIT_V(8); PG8_WAIT_L(0); PG8_BAR; PG8_MMA(0, 0, At, B0); PG8_MMA(0, 1, At, B1); PG8_BAR; PG8_SCHED;
	s_waitcnt lgkmcnt(0)
	v_mfma_f32_16x16x32_bf16 v[66:69], v[168:171], v[214:217], v[66:69]
	v_mfma_f32_16x16x32_bf16 v[62:65], v[190:193], v[214:217], v[62:65]
	v_mfma_f32_16x16x32_bf16 v[50:53], v[168:171], v[222:225], v[50:53]
	v_mfma_f32_16x16x32_bf16 v[46:49], v[190:193], v[222:225], v[46:49]
	v_mfma_f32_16x16x32_bf16 v[34:37], v[168:171], v[230:233], v[34:37]
	v_mfma_f32_16x16x32_bf16 v[30:33], v[190:193], v[230:233], v[30:33]
	v_mfma_f32_16x16x32_bf16 v[18:21], v[168:171], v[238:241], v[18:21]
	v_mfma_f32_16x16x32_bf16 v[14:17], v[190:193], v[238:241], v[14:17]
	v_mfma_f32_16x16x32_bf16 v[66:69], v[186:189], v[218:221], v[66:69]
	v_mfma_f32_16x16x32_bf16 v[62:65], v[194:197], v[218:221], v[62:65]
	v_mfma_f32_16x16x32_bf16 v[50:53], v[186:189], v[226:229], v[50:53]
	v_mfma_f32_16x16x32_bf16 v[46:49], v[194:197], v[226:229], v[46:49]
	v_mfma_f32_16x16x32_bf16 v[34:37], v[186:189], v[234:237], v[34:37]
	v_mfma_f32_16x16x32_bf16 v[30:33], v[194:197], v[234:237], v[30:33]
	v_mfma_f32_16x16x32_bf16 v[18:21], v[186:189], v[242:245], v[18:21]
	v_mfma_f32_16x16x32_bf16 v[14:17], v[194:197], v[242:245], v[14:17]
	v_mfma_f32_16x16x32_bf16 v[58:61], v[198:201], v[214:217], v[58:61]
	v_mfma_f32_16x16x32_bf16 v[54:57], v[206:209], v[214:217], v[54:57]
	v_mfma_f32_16x16x32_bf16 v[42:45], v[198:201], v[222:225], v[42:45]
	v_mfma_f32_16x16x32_bf16 v[38:41], v[206:209], v[222:225], v[38:41]
	v_mfma_f32_16x16x32_bf16 v[26:29], v[198:201], v[230:233], v[26:29]
	v_mfma_f32_16x16x32_bf16 v[22:25], v[206:209], v[230:233], v[22:25]
	v_mfma_f32_16x16x32_bf16 v[10:13], v[198:201], v[238:241], v[10:13]
	v_mfma_f32_16x16x32_bf16 v[4:7], v[206:209], v[238:241], v[6:9]
	v_mfma_f32_16x16x32_bf16 v[58:61], v[202:205], v[218:221], v[58:61]
	v_mfma_f32_16x16x32_bf16 v[54:57], v[210:213], v[218:221], v[54:57]
	v_mfma_f32_16x16x32_bf16 v[42:45], v[202:205], v[226:229], v[42:45]
	v_mfma_f32_16x16x32_bf16 v[38:41], v[210:213], v[226:229], v[38:41]
	v_mfma_f32_16x16x32_bf16 v[26:29], v[202:205], v[234:237], v[26:29]
	v_mfma_f32_16x16x32_bf16 v[22:25], v[210:213], v[234:237], v[22:25]
	v_mfma_f32_16x16x32_bf16 v[10:13], v[202:205], v[242:245], v[10:13]
	v_mfma_f32_16x16x32_bf16 v[4:7], v[210:213], v[242:245], v[4:7]
	s_barrier
	s_add_i32 s14, 0, 0x18000
	v_add_u32_e32 v3, s14, v172
	s_add_i32 s15, 0, 0x1c000
	ds_read_b128 v[168:171], v3
	ds_read_b128 v[186:189], v3 offset:1024
	ds_read_b128 v[190:193], v3 offset:2048
	ds_read_b128 v[194:197], v3 offset:3072
	v_add_u32_e32 v3, s15, v172
	ds_read_b128 v[198:201], v3
	ds_read_b128 v[202:205], v3 offset:1024
	ds_read_b128 v[206:209], v3 offset:2048
	ds_read_b128 v[210:213], v3 offset:3072
	s_add_u32 s12, s12, 0x100000
	s_addc_u32 s13, s13, 0
	s_mov_b32 m0, s61
	v_lshl_add_u64 v[8:9], s[12:13], 0, v[150:151]
	ds_read_b128 v[214:217], v182 offset:32768
	ds_read_b128 v[218:221], v182 offset:33792
	ds_read_b128 v[222:225], v182 offset:34816
	ds_read_b128 v[226:229], v182 offset:35840
	ds_read_b128 v[230:233], v182 offset:36864
	ds_read_b128 v[234:237], v182 offset:37888
	ds_read_b128 v[238:241], v182 offset:38912
	ds_read_b128 v[242:245], v182 offset:39936
	global_load_lds_dwordx4 v[8:9], off
	v_lshl_add_u64 v[8:9], s[12:13], 0, v[152:153]
	s_mov_b32 m0, s62
	s_nop 0
	global_load_lds_dwordx4 v[8:9], off
	s_waitcnt vmcnt(8)
	s_waitcnt lgkmcnt(0)
	s_barrier
	s_waitcnt lgkmcnt(0)
	v_mfma_f32_16x16x32_bf16 v[130:133], v[168:171], v[214:217], v[130:133]
	v_mfma_f32_16x16x32_bf16 v[126:129], v[190:193], v[214:217], v[126:129]
	v_mfma_f32_16x16x32_bf16 v[114:117], v[168:171], v[222:225], v[114:117]
	v_mfma_f32_16x16x32_bf16 v[110:113], v[190:193], v[222:225], v[110:113]
	v_mfma_f32_16x16x32_bf16 v[98:101], v[168:171], v[230:233], v[98:101]
	v_mfma_f32_16x16x32_bf16 v[94:97], v[190:193], v[230:233], v[94:97]
	v_mfma_f32_16x16x32_bf16 v[82:85], v[168:171], v[238:241], v[82:85]
	v_mfma_f32_16x16x32_bf16 v[78:81], v[190:193], v[238:241], v[78:81]
	v_mfma_f32_16x16x32_bf16 v[130:133], v[186:189], v[218:221], v[130:133]
	v_mfma_f32_16x16x32_bf16 v[126:129], v[194:197], v[218:221], v[126:129]
	v_mfma_f32_16x16x32_bf16 v[114:117], v[186:189], v[226:229], v[114:117]
	v_mfma_f32_16x16x32_bf16 v[110:113], v[194:197], v[226:229], v[110:113]
	v_mfma_f32_16x16x32_bf16 v[98:101], v[186:189], v[234:237], v[98:101]
	v_mfma_f32_16x16x32_bf16 v[94:97], v[194:197], v[234:237], v[94:97]
	v_mfma_f32_16x16x32_bf16 v[82:85], v[186:189], v[242:245], v[82:85]
	v_mfma_f32_16x16x32_bf16 v[78:81], v[194:197], v[242:245], v[78:81]
	v_mfma_f32_16x16x32_bf16 v[122:125], v[198:201], v[214:217], v[122:125]
	v_mfma_f32_16x16x32_bf16 v[118:121], v[206:209], v[214:217], v[118:121]
	v_mfma_f32_16x16x32_bf16 v[106:109], v[198:201], v[222:225], v[106:109]
	v_mfma_f32_16x16x32_bf16 v[102:105], v[206:209], v[222:225], v[102:105]
	v_mfma_f32_16x16x32_bf16 v[90:93], v[198:201], v[230:233], v[90:93]
	v_mfma_f32_16x16x32_bf16 v[86:89], v[206:209], v[230:233], v[86:89]
	v_mfma_f32_16x16x32_bf16 v[74:77], v[198:201], v[238:241], v[74:77]
	v_mfma_f32_16x16x32_bf16 v[70:73], v[206:209], v[238:241], v[70:73]
	v_mfma_f32_16x16x32_bf16 v[122:125], v[202:205], v[218:221], v[122:125]
	v_mfma_f32_16x16x32_bf16 v[118:121], v[210:213], v[218:221], v[118:121]
	v_mfma_f32_16x16x32_bf16 v[106:109], v[202:205], v[226:229], v[106:109]
	v_mfma_f32_16x16x32_bf16 v[102:105], v[210:213], v[226:229], v[102:105]
	v_mfma_f32_16x16x32_bf16 v[90:93], v[202:205], v[234:237], v[90:93]
	v_mfma_f32_16x16x32_bf16 v[86:89], v[210:213], v[234:237], v[86:89]
	v_mfma_f32_16x16x32_bf16 v[74:77], v[202:205], v[242:245], v[74:77]
	v_mfma_f32_16x16x32_bf16 v[70:73], v[210:213], v[242:245], v[70:73]
	s_barrier
; #define PG8_STAGE(bufoff, gbase, voff) do { _Pragma("unroll") for (int _i = 0; _i < 2; ++_i) \
;         __builtin_amdgcn_global_load_lds((const unsigned*)((const char*)(gbase) + (voff)[_i]), (PG8_LAS unsigned*)(lds + (bufoff) + ldsw + _i * 8192), 16, 0, 0); } while (0)
; #define PG8_LDA(dst, b, h) do { _Pragma("unroll") for (int m = 0; m < 4; ++m) _Pragma("unroll") for (int k = 0; k < 2; ++k) dst[m][k] = *(const PG8_LAS bf16x8*)(lds + PG8_SA(b, h) + aoff + m * 2048 + k * 1024); } while (0)
; #define PG8_WAIT_V(n) asm volatile("s_waitcnt vmcnt(" #n ")" ::: "memory")
; #define PG8_WAIT_L(n) asm volatile("s_waitcnt lgkmcnt(" #n ")" ::: "memory")
; #define PG8_BAR __builtin_amdgcn_s_barrier()
; #define PG8_SCHED __builtin_amdgcn_sched_barrier(0)
; template <class Epi, class Sched, bool ALIGN_EPI = false, bool SP2 = false>
; __device__ __forceinline__ void gemm_phase(PG8_LAS unsigned char* lds, const Gemm g, const Sched& S, const Epi& E) {
;     ...
;             PG8_LDA(At, 1, 1); PG8_STAGE(PG8_SB(1, 0), b3, voffB); PG8_STAGE(PG8_SB(1, 1), b3 + hstep, voffB); PG8_STAGE(PG8_SA(1, 0), a3, voffA);
;             PG8_WAIT_V(8); PG8_WAIT_L(0); PG8_BAR; PG8_MMA(1, 0, At, B0); PG8_MMA(1, 1, At, B1); PG8_BAR; PG8_SCHED;
	s_add_i32 s12, s14, s59
	v_lshl_add_u64 v[8:9], v[246:247], 0, s[38:39]
	s_mov_b32 m0, s12
	ds_read_b128 v[214:217], v182 offset:49152
	ds_read_b128 v[218:221], v182 offset:50176
	ds_read_b128 v[222:225], v182 offset:51200
	ds_read_b128 v[226:229], v182 offset:52224
	ds_read_b128 v[230:233], v182 offset:53248
	ds_read_b128 v[234:237], v182 offset:54272
	ds_read_b128 v[238:241], v182 offset:55296
	ds_read_b128 v[242:245], v182 offset:56320
	global_load_lds_dwordx4 v[8:9], off
	s_add_i32 m0, s12, 0x2000
	s_add_u32 s10, s10, 0x100080
	v_lshl_add_u64 v[8:9], v[248:249], 0, s[38:39]
	s_addc_u32 s11, s11, 0
	s_add_i32 s12, s15, s59
	global_load_lds_dwordx4 v[8:9], off
	v_lshl_add_u64 v[8:9], s[10:11], 0, v[150:151]
	s_mov_b32 m0, s12
	s_nop 0
	global_load_lds_dwordx4 v[8:9], off
	v_lshl_add_u64 v[8:9], s[10:11], 0, v[152:153]
	s_add_i32 m0, s12, 0x2000
	s_nop 0
	global_load_lds_dwordx4 v[8:9], off
	v_lshl_add_u64 v[8:9], v[250:251], 0, s[38:39]
	s_mov_b32 m0, s64
	s_nop 0
	global_load_lds_dwordx4 v[8:9], off
	v_lshl_add_u64 v[8:9], v[252:253], 0, s[38:39]
	s_mov_b32 m0, s65
	s_nop 0
	global_load_lds_dwordx4 v[8:9], off
	s_waitcnt vmcnt(8)
	s_waitcnt lgkmcnt(0)
	s_barrier
	s_waitcnt lgkmcnt(0)
	v_mfma_f32_16x16x32_bf16 v[66:69], v[168:171], v[214:217], v[66:69]
	v_mfma_f32_16x16x32_bf16 v[62:65], v[190:193], v[214:217], v[62:65]
	v_mfma_f32_16x16x32_bf16 v[50:53], v[168:171], v[222:225], v[50:53]
	v_mfma_f32_16x16x32_bf16 v[46:49], v[190:193], v[222:225], v[46:49]
	v_mfma_f32_16x16x32_bf16 v[34:37], v[168:171], v[230:233], v[34:37]
	v_mfma_f32_16x16x32_bf16 v[30:33], v[190:193], v[230:233], v[30:33]
	v_mfma_f32_16x16x32_bf16 v[18:21], v[168:171], v[238:241], v[18:21]
	v_mfma_f32_16x16x32_bf16 v[14:17], v[190:193], v[238:241], v[14:17]
	v_mfma_f32_16x16x32_bf16 v[66:69], v[186:189], v[218:221], v[66:69]
	v_mfma_f32_16x16x32_bf16 v[62:65], v[194:197], v[218:221], v[62:65]
	v_mfma_f32_16x16x32_bf16 v[50:53], v[186:189], v[226:229], v[50:53]
	v_mfma_f32_16x16x32_bf16 v[46:49], v[194:197], v[226:229], v[46:49]
	v_mfma_f32_16x16x32_bf16 v[34:37], v[186:189], v[234:237], v[34:37]
	v_mfma_f32_16x16x32_bf16 v[30:33], v[194:197], v[234:237], v[30:33]
	v_mfma_f32_16x16x32_bf16 v[18:21], v[186:189], v[242:245], v[18:21]
	v_mfma_f32_16x16x32_bf16 v[14:17], v[194:197], v[242:245], v[14:17]
	v_mfma_f32_16x16x32_bf16 v[58:61], v[198:201], v[214:217], v[58:61]
	v_mfma_f32_16x16x32_bf16 v[54:57], v[206:209], v[214:217], v[54:57]
	v_mfma_f32_16x16x32_bf16 v[42:45], v[198:201], v[222:225], v[42:45]
	v_mfma_f32_16x16x32_bf16 v[38:41], v[206:209], v[222:225], v[38:41]
	v_mfma_f32_16x16x32_bf16 v[26:29], v[198:201], v[230:233], v[26:29]
	v_mfma_f32_16x16x32_bf16 v[22:25], v[206:209], v[230:233], v[22:25]
	v_mfma_f32_16x16x32_bf16 v[8:11], v[198:201], v[238:241], v[10:13]
	v_mfma_f32_16x16x32_bf16 v[4:7], v[206:209], v[238:241], v[4:7]
	v_mfma_f32_16x16x32_bf16 v[58:61], v[202:205], v[218:221], v[58:61]
	v_mfma_f32_16x16x32_bf16 v[54:57], v[210:213], v[218:221], v[54:57]
	v_mfma_f32_16x16x32_bf16 v[42:45], v[202:205], v[226:229], v[42:45]
	v_mfma_f32_16x16x32_bf16 v[38:41], v[210:213], v[226:229], v[38:41]
	v_mfma_f32_16x16x32_bf16 v[26:29], v[202:205], v[234:237], v[26:29]
	v_mfma_f32_16x16x32_bf16 v[22:25], v[210:213], v[234:237], v[22:25]
	v_mfma_f32_16x16x32_bf16 v[10:13], v[202:205], v[242:245], v[8:11]
	v_mfma_f32_16x16x32_bf16 v[6:9], v[210:213], v[242:245], v[4:7]
	s_barrier
	s_add_i32 s73, s73, 2
	s_add_u32 s54, s54, 0x100
	s_addc_u32 s55, s55, 0
	s_cmp_gt_u32 s73, 61
	s_cbranch_scc1 .LBB0_1135

; #define PG8_STAGE(bufoff, gbase, voff) do { _Pragma("unroll") for (int _i = 0; _i < 2; ++_i) \
;         __builtin_amdgcn_global_load_lds((const unsigned*)((const char*)(gbase) + (voff)[_i]), (PG8_LAS unsigned*)(lds + (bufoff) + ldsw + _i * 8192), 16, 0, 0); } while (0)
; #define PG8_LDA(dst, b, h) do { _Pragma("unroll") for (int m = 0; m < 4; ++m) _Pragma("unroll") for (int k = 0; k < 2; ++k) dst[m][k] = *(const PG8_LAS bf16x8*)(lds + PG8_SA(b, h) + aoff + m * 2048 + k * 1024); } while (0)
; #define PG8_LDB(dst, b, h) do { _Pragma("unroll") for (int n = 0; n < 2; ++n) _Pragma("unroll") for (int k = 0; k < 2; ++k) dst[n][k] = *(const PG8_LAS bf16x8*)(lds + PG8_SB(b, h) + boff + n * 2048 + k * 1024); } while (0)
; #define PG8_WAIT_V(n) asm volatile("s_waitcnt vmcnt(" #n ")" ::: "memory")
; #define PG8_WAIT_L(n) asm volatile("s_waitcnt lgkmcnt(" #n ")" ::: "memory")
; #define PG8_BAR __builtin_amdgcn_s_barrier()
; #define PG8_SCHED __builtin_amdgcn_sched_barrier(0)
; template <class Epi, class Sched, bool ALIGN_EPI = false, bool SP2 = false>
; __device__ __forceinline__ void gemm_phase(PG8_LAS unsigned char* lds, const Gemm g, const Sched& S, const Epi& E) {
;     ...
;             PG8_LDB(B0, 0, 0); PG8_LDB(B1, 0, 1); PG8_SCHED; PG8_LDA(At, 0, 0); PG8_STAGE(PG8_SA(1, 1), a1 + hstep, voffA);
;             PG8_WAIT_V(8); PG8_WAIT_L(0); PG8_BAR; PG8_MMA(0, 0, At, B0); PG8_MMA(0, 1, At, B1); PG8_BAR; PG8_SCHED;
;             PG8_LDA(At, 0, 1); PG8_STAGE(PG8_SB(0, 0), b2, voffB); PG8_STAGE(PG8_SB(0, 1), b2 + hstep, voffB); PG8_STAGE(PG8_SA(0, 0), a2, voffA);
;             PG8_WAIT_V(8); PG8_WAIT_L(0); PG8_BAR; PG8_MMA(1, 0, At, B0); PG8_MMA(1, 1, At, B1); PG8_BAR; PG8_SCHED;
.LBB0_1233:
	ds_read_b128 v[150:153], v213
	ds_read_b128 v[154:157], v213 offset:1024
	ds_read_b128 v[158:161], v213 offset:2048
	ds_read_b128 v[162:165], v213 offset:3072
	ds_read_b128 v[166:169], v214
	ds_read_b128 v[170:173], v214 offset:1024
	ds_read_b128 v[174:177], v214 offset:2048
	ds_read_b128 v[178:181], v214 offset:3072
	s_add_u32 s16, s22, 0x100
	s_addc_u32 s17, s23, 0
	s_cmp_eq_u32 s27, 28
	s_cselect_b32 s25, s53, s17
	s_cselect_b32 s24, s52, s16
	s_cselect_b32 s19, s1, s26
	s_cselect_b32 s18, s5, s21
	v_lshl_add_u64 v[190:191], s[22:23], 0, v[142:143]
	s_add_i32 m0, s63, 0xc000
	ds_read_b128 v[182:185], v215
	ds_read_b128 v[186:189], v215 offset:1024
	ds_read_b128 v[218:221], v215 offset:2048
	ds_read_b128 v[222:225], v215 offset:3072
	ds_read_b128 v[226:229], v215 offset:4096
	ds_read_b128 v[230:233], v215 offset:5120
	ds_read_b128 v[234:237], v215 offset:6144
	ds_read_b128 v[238:241], v215 offset:7168
	global_load_lds_dwordx4 v[190:191], off
	v_lshl_add_u64 v[190:191], s[22:23], 0, v[144:145]
	s_add_i32 m0, s63, 0xe000
	s_nop 0
	global_load_lds_dwordx4 v[190:191], off
	s_waitcnt vmcnt(8)
	s_waitcnt lgkmcnt(0)
	s_barrier
	s_waitcnt lgkmcnt(0)
	v_mfma_i32_16x16x64_i8 v[62:65], v[150:153], v[182:185], v[62:65]
	v_mfma_i32_16x16x64_i8 v[46:49], v[158:161], v[182:185], v[46:49]
	v_mfma_i32_16x16x64_i8 v[58:61], v[150:153], v[218:221], v[58:61]
	v_mfma_i32_16x16x64_i8 v[42:45], v[158:161], v[218:221], v[42:45]
	v_mfma_i32_16x16x64_i8 v[114:117], v[150:153], v[226:229], v[114:117]
	v_mfma_i32_16x16x64_i8 v[110:113], v[158:161], v[226:229], v[110:113]
	v_mfma_i32_16x16x64_i8 v[126:129], v[150:153], v[234:237], v[126:129]
	v_mfma_i32_16x16x64_i8 v[106:109], v[158:161], v[234:237], v[106:109]
	v_mfma_i32_16x16x64_i8 v[62:65], v[154:157], v[186:189], v[62:65]
	v_mfma_i32_16x16x64_i8 v[46:49], v[162:165], v[186:189], v[46:49]
	v_mfma_i32_16x16x64_i8 v[58:61], v[154:157], v[222:225], v[58:61]
	v_mfma_i32_16x16x64_i8 v[42:45], v[162:165], v[222:225], v[42:45]
	v_mfma_i32_16x16x64_i8 v[114:117], v[154:157], v[230:233], v[114:117]
	v_mfma_i32_16x16x64_i8 v[110:113], v[162:165], v[230:233], v[110:113]
	v_mfma_i32_16x16x64_i8 v[126:129], v[154:157], v[238:241], v[126:129]
	v_mfma_i32_16x16x64_i8 v[106:109], v[162:165], v[238:241], v[106:109]
	v_mfma_i32_16x16x64_i8 v[54:57], v[166:169], v[182:185], v[54:57]
	v_mfma_i32_16x16x64_i8 v[38:41], v[174:177], v[182:185], v[38:41]
	v_mfma_i32_16x16x64_i8 v[50:53], v[166:169], v[218:221], v[50:53]
	v_mfma_i32_16x16x64_i8 v[34:37], v[174:177], v[218:221], v[34:37]
	v_mfma_i32_16x16x64_i8 v[122:125], v[166:169], v[226:229], v[122:125]
	v_mfma_i32_16x16x64_i8 v[102:105], v[174:177], v[226:229], v[102:105]
	v_mfma_i32_16x16x64_i8 v[118:121], v[166:169], v[234:237], v[118:121]
	v_mfma_i32_16x16x64_i8 v[98:101], v[174:177], v[234:237], v[98:101]
	v_mfma_i32_16x16x64_i8 v[54:57], v[170:173], v[186:189], v[54:57]
	v_mfma_i32_16x16x64_i8 v[38:41], v[178:181], v[186:189], v[38:41]
	v_mfma_i32_16x16x64_i8 v[50:53], v[170:173], v[222:225], v[50:53]
	v_mfma_i32_16x16x64_i8 v[34:37], v[178:181], v[222:225], v[34:37]
	v_mfma_i32_16x16x64_i8 v[122:125], v[170:173], v[230:233], v[122:125]
	v_mfma_i32_16x16x64_i8 v[102:105], v[178:181], v[230:233], v[102:105]
	v_mfma_i32_16x16x64_i8 v[118:121], v[170:173], v[238:241], v[118:121]
	v_mfma_i32_16x16x64_i8 v[98:101], v[178:181], v[238:241], v[98:101]
	s_barrier
	s_add_i32 s22, s73, s62
	v_lshl_add_u64 v[190:191], s[18:19], 0, v[130:131]
	s_mov_b32 m0, s22
	ds_read_b128 v[182:185], v215 offset:16384
	ds_read_b128 v[186:189], v215 offset:17408
	ds_read_b128 v[218:221], v215 offset:18432
	ds_read_b128 v[222:225], v215 offset:19456
	ds_read_b128 v[226:229], v215 offset:20480
	ds_read_b128 v[230:233], v215 offset:21504
	ds_read_b128 v[234:237], v215 offset:22528
	ds_read_b128 v[238:241], v215 offset:23552
	global_load_lds_dwordx4 v[190:191], off
	s_add_i32 m0, s22, 0x2000
	s_add_u32 s22, s18, 0x80000
	v_lshl_add_u64 v[242:243], s[18:19], 0, v[136:137]
	s_addc_u32 s23, s19, 0
	s_add_i32 s28, s75, s62
	global_load_lds_dwordx4 v[242:243], off
	v_lshl_add_u64 v[244:245], s[22:23], 0, v[130:131]
	s_mov_b32 m0, s28
	v_lshl_add_u64 v[246:247], s[24:25], 0, v[134:135]
	global_load_lds_dwordx4 v[244:245], off
	v_lshl_add_u64 v[244:245], s[22:23], 0, v[136:137]
	s_add_i32 m0, s28, 0x2000
	s_nop 0
	global_load_lds_dwordx4 v[244:245], off
	v_lshl_add_u64 v[244:245], s[24:25], 0, v[132:133]
	s_mov_b32 m0, s63
	s_nop 0
	global_load_lds_dwordx4 v[244:245], off
	s_mov_b32 m0, s64
	s_nop 0
	global_load_lds_dwordx4 v[246:247], off
	s_waitcnt vmcnt(8)
	s_waitcnt lgkmcnt(0)
	s_barrier
; #define PG8_STAGE(bufoff, gbase, voff) do { _Pragma("unroll") for (int _i = 0; _i < 2; ++_i) \
;         __builtin_amdgcn_global_load_lds((const unsigned*)((const char*)(gbase) + (voff)[_i]), (PG8_LAS unsigned*)(lds + (bufoff) + ldsw + _i * 8192), 16, 0, 0); } while (0)
; #define PG8_LDA(dst, b, h) do { _Pragma("unroll") for (int m = 0; m < 4; ++m) _Pragma("unroll") for (int k = 0; k < 2; ++k) dst[m][k] = *(const PG8_LAS bf16x8*)(lds + PG8_SA(b, h) + aoff + m * 2048 + k * 1024); } while (0)
; #define PG8_LDB(dst, b, h) do { _Pragma("unroll") for (int n = 0; n < 2; ++n) _Pragma("unroll") for (int k = 0; k < 2; ++k) dst[n][k] = *(const PG8_LAS bf16x8*)(lds + PG8_SB(b, h) + boff + n * 2048 + k * 1024); } while (0)
; #define PG8_WAIT_V(n) asm volatile("s_waitcnt vmcnt(" #n ")" ::: "memory")
; #define PG8_WAIT_L(n) asm volatile("s_waitcnt lgkmcnt(" #n ")" ::: "memory")
; #define PG8_BAR __builtin_amdgcn_s_barrier()
; #define PG8_SCHED __builtin_amdgcn_sched_barrier(0)
; template <class Epi, class Sched, bool ALIGN_EPI = false, bool SP2 = false>
; __device__ __forceinline__ void gemm_phase(PG8_LAS unsigned char* lds, const Gemm g, const Sched& S, const Epi& E) {
;     ...
;             PG8_WAIT_V(8); PG8_WAIT_L(0); PG8_BAR; PG8_MMA(1, 0, At, B0); PG8_MMA(1, 1, At, B1); PG8_BAR; PG8_SCHED;
;             PG8_LDB(B0, 1, 0); PG8_LDB(B1, 1, 1); PG8_SCHED; PG8_LDA(At, 1, 0); PG8_STAGE(PG8_SA(0, 1), a2 + hstep, voffA);
;             PG8_WAIT_V(8); PG8_WAIT_L(0); PG8_BAR; PG8_MMA(0, 0, At, B0); PG8_MMA(0, 1, At, B1); PG8_BAR; PG8_SCHED;
	s_waitcnt lgkmcnt(0)
	v_mfma_i32_16x16x64_i8 v[30:33], v[150:153], v[182:185], v[30:33]
	v_mfma_i32_16x16x64_i8 v[14:17], v[158:161], v[182:185], v[14:17]
	v_mfma_i32_16x16x64_i8 v[26:29], v[150:153], v[218:221], v[26:29]
	v_mfma_i32_16x16x64_i8 v[10:13], v[158:161], v[218:221], v[10:13]
	v_mfma_i32_16x16x64_i8 v[94:97], v[150:153], v[226:229], v[94:97]
	v_mfma_i32_16x16x64_i8 v[90:93], v[158:161], v[226:229], v[90:93]
	v_mfma_i32_16x16x64_i8 v[86:89], v[150:153], v[234:237], v[86:89]
	v_mfma_i32_16x16x64_i8 v[82:85], v[158:161], v[234:237], v[82:85]
	v_mfma_i32_16x16x64_i8 v[30:33], v[154:157], v[186:189], v[30:33]
	v_mfma_i32_16x16x64_i8 v[14:17], v[162:165], v[186:189], v[14:17]
	v_mfma_i32_16x16x64_i8 v[26:29], v[154:157], v[222:225], v[26:29]
	v_mfma_i32_16x16x64_i8 v[10:13], v[162:165], v[222:225], v[10:13]
	v_mfma_i32_16x16x64_i8 v[94:97], v[154:157], v[230:233], v[94:97]
	v_mfma_i32_16x16x64_i8 v[90:93], v[162:165], v[230:233], v[90:93]
	v_mfma_i32_16x16x64_i8 v[86:89], v[154:157], v[238:241], v[86:89]
	v_mfma_i32_16x16x64_i8 v[82:85], v[162:165], v[238:241], v[82:85]
	v_mfma_i32_16x16x64_i8 v[22:25], v[166:169], v[182:185], v[22:25]
	v_mfma_i32_16x16x64_i8 v[6:9], v[174:177], v[182:185], v[6:9]
	v_mfma_i32_16x16x64_i8 v[18:21], v[166:169], v[218:221], v[18:21]
	v_mfma_i32_16x16x64_i8 v[2:5], v[174:177], v[218:221], v[2:5]
	v_mfma_i32_16x16x64_i8 v[78:81], v[166:169], v[226:229], v[78:81]
	v_mfma_i32_16x16x64_i8 v[74:77], v[174:177], v[226:229], v[74:77]
	v_mfma_i32_16x16x64_i8 v[70:73], v[166:169], v[234:237], v[70:73]
	v_mfma_i32_16x16x64_i8 v[66:69], v[174:177], v[234:237], v[66:69]
	v_mfma_i32_16x16x64_i8 v[22:25], v[170:173], v[186:189], v[22:25]
	v_mfma_i32_16x16x64_i8 v[6:9], v[178:181], v[186:189], v[6:9]
	v_mfma_i32_16x16x64_i8 v[18:21], v[170:173], v[222:225], v[18:21]
	v_mfma_i32_16x16x64_i8 v[2:5], v[178:181], v[222:225], v[2:5]
	v_mfma_i32_16x16x64_i8 v[78:81], v[170:173], v[230:233], v[78:81]
	v_mfma_i32_16x16x64_i8 v[74:77], v[178:181], v[230:233], v[74:77]
	v_mfma_i32_16x16x64_i8 v[70:73], v[170:173], v[238:241], v[70:73]
	v_mfma_i32_16x16x64_i8 v[66:69], v[178:181], v[238:241], v[66:69]
	s_barrier
	s_add_i32 s28, 0, 0x18000
	s_add_i32 s29, 0, 0x1c000
	v_add_u32_e32 v162, s28, v1
	v_add_u32_e32 v178, s29, v1
	ds_read_b128 v[150:153], v162
	ds_read_b128 v[154:157], v162 offset:1024
	ds_read_b128 v[158:161], v162 offset:2048
	ds_read_b128 v[162:165], v162 offset:3072
	ds_read_b128 v[166:169], v178
	ds_read_b128 v[170:173], v178 offset:1024
	ds_read_b128 v[174:177], v178 offset:2048
	ds_read_b128 v[178:181], v178 offset:3072
	s_add_u32 s22, s24, 0x80000
	s_addc_u32 s23, s25, 0
	s_mov_b32 m0, s65
	v_lshl_add_u64 v[248:249], s[22:23], 0, v[132:133]
	ds_read_b128 v[182:185], v215 offset:32768
	ds_read_b128 v[186:189], v215 offset:33792
	ds_read_b128 v[218:221], v215 offset:34816
	ds_read_b128 v[222:225], v215 offset:35840
	ds_read_b128 v[226:229], v215 offset:36864
	ds_read_b128 v[230:233], v215 offset:37888
	ds_read_b128 v[234:237], v215 offset:38912
	ds_read_b128 v[238:241], v215 offset:39936
	global_load_lds_dwordx4 v[248:249], off
	v_lshl_add_u64 v[248:249], s[22:23], 0, v[134:135]
	s_mov_b32 m0, s66
	s_nop 0
	global_load_lds_dwordx4 v[248:249], off
	s_waitcnt vmcnt(8)
	s_waitcnt lgkmcnt(0)
	s_barrier
	s_waitcnt lgkmcnt(0)
	v_mfma_i32_16x16x64_i8 v[62:65], v[150:153], v[182:185], v[62:65]
	v_mfma_i32_16x16x64_i8 v[46:49], v[158:161], v[182:185], v[46:49]
	v_mfma_i32_16x16x64_i8 v[58:61], v[150:153], v[218:221], v[58:61]
	v_mfma_i32_16x16x64_i8 v[42:45], v[158:161], v[218:221], v[42:45]
	v_mfma_i32_16x16x64_i8 v[114:117], v[150:153], v[226:229], v[114:117]
	v_mfma_i32_16x16x64_i8 v[110:113], v[158:161], v[226:229], v[110:113]
	v_mfma_i32_16x16x64_i8 v[126:129], v[150:153], v[234:237], v[126:129]
	v_mfma_i32_16x16x64_i8 v[106:109], v[158:161], v[234:237], v[106:109]
	v_mfma_i32_16x16x64_i8 v[62:65], v[154:157], v[186:189], v[62:65]
	v_mfma_i32_16x16x64_i8 v[46:49], v[162:165], v[186:189], v[46:49]
	v_mfma_i32_16x16x64_i8 v[58:61], v[154:157], v[222:225], v[58:61]
	v_mfma_i32_16x16x64_i8 v[42:45], v[162:165], v[222:225], v[42:45]
	v_mfma_i32_16x16x64_i8 v[114:117], v[154:157], v[230:233], v[114:117]
	v_mfma_i32_16x16x64_i8 v[110:113], v[162:165], v[230:233], v[110:113]
	v_mfma_i32_16x16x64_i8 v[126:129], v[154:157], v[238:241], v[126:129]
	v_mfma_i32_16x16x64_i8 v[106:109], v[162:165], v[238:241], v[106:109]
	v_mfma_i32_16x16x64_i8 v[54:57], v[166:169], v[182:185], v[54:57]
	v_mfma_i32_16x16x64_i8 v[38:41], v[174:177], v[182:185], v[38:41]
	v_mfma_i32_16x16x64_i8 v[50:53], v[166:169], v[218:221], v[50:53]
	v_mfma_i32_16x16x64_i8 v[34:37], v[174:177], v[218:221], v[34:37]
	v_mfma_i32_16x16x64_i8 v[122:125], v[166:169], v[226:229], v[122:125]
	v_mfma_i32_16x16x64_i8 v[102:105], v[174:177], v[226:229], v[102:105]
	v_mfma_i32_16x16x64_i8 v[118:121], v[166:169], v[234:237], v[118:121]
	v_mfma_i32_16x16x64_i8 v[98:101], v[174:177], v[234:237], v[98:101]
	v_mfma_i32_16x16x64_i8 v[54:57], v[170:173], v[186:189], v[54:57]
	v_mfma_i32_16x16x64_i8 v[38:41], v[178:181], v[186:189], v[38:41]
	v_mfma_i32_16x16x64_i8 v[50:53], v[170:173], v[222:225], v[50:53]
	v_mfma_i32_16x16x64_i8 v[34:37], v[178:181], v[222:225], v[34:37]
	v_mfma_i32_16x16x64_i8 v[122:125], v[170:173], v[230:233], v[122:125]
	v_mfma_i32_16x16x64_i8 v[102:105], v[178:181], v[230:233], v[102:105]
	v_mfma_i32_16x16x64_i8 v[118:121], v[170:173], v[238:241], v[118:121]
	v_mfma_i32_16x16x64_i8 v[98:101], v[178:181], v[238:241], v[98:101]
	s_barrier
; #define PG8_STAGE(bufoff, gbase, voff) do { _Pragma("unroll") for (int _i = 0; _i < 2; ++_i) \
;         __builtin_amdgcn_global_load_lds((const unsigned*)((const char*)(gbase) + (voff)[_i]), (PG8_LAS unsigned*)(lds + (bufoff) + ldsw + _i * 8192), 16, 0, 0); } while (0)
; #define PG8_LDA(dst, b, h) do { _Pragma("unroll") for (int m = 0; m < 4; ++m) _Pragma("unroll") for (int k = 0; k < 2; ++k) dst[m][k] = *(const PG8_LAS bf16x8*)(lds + PG8_SA(b, h) + aoff + m * 2048 + k * 1024); } while (0)
; #define PG8_WAIT_V(n) asm volatile("s_waitcnt vmcnt(" #n ")" ::: "memory")
; #define PG8_WAIT_L(n) asm volatile("s_waitcnt lgkmcnt(" #n ")" ::: "memory")
; #define PG8_BAR __builtin_amdgcn_s_barrier()
; #define PG8_SCHED __builtin_amdgcn_sched_barrier(0)
; template <class Epi, class Sched, bool ALIGN_EPI = false, bool SP2 = false>
; __device__ __forceinline__ void gemm_phase(PG8_LAS unsigned char* lds, const Gemm g, const Sched& S, const Epi& E) {
;     ...
;             PG8_LDA(At, 1, 1); PG8_STAGE(PG8_SB(1, 0), b3, voffB); PG8_STAGE(PG8_SB(1, 1), b3 + hstep, voffB); PG8_STAGE(PG8_SA(1, 0), a3, voffA);
;             PG8_WAIT_V(8); PG8_WAIT_L(0); PG8_BAR; PG8_MMA(1, 0, At, B0); PG8_MMA(1, 1, At, B1); PG8_BAR; PG8_SCHED;
	s_add_i32 s22, s28, s62
	v_lshl_add_u64 v[190:191], v[190:191], 0, s[42:43]
	s_mov_b32 m0, s22
	ds_read_b128 v[182:185], v215 offset:49152
	ds_read_b128 v[186:189], v215 offset:50176
	ds_read_b128 v[218:221], v215 offset:51200
	ds_read_b128 v[222:225], v215 offset:52224
	ds_read_b128 v[226:229], v215 offset:53248
	ds_read_b128 v[230:233], v215 offset:54272
	ds_read_b128 v[234:237], v215 offset:55296
	ds_read_b128 v[238:241], v215 offset:56320
	global_load_lds_dwordx4 v[190:191], off
	s_add_i32 m0, s22, 0x2000
	s_add_u32 s18, s18, 0x80080
	v_lshl_add_u64 v[190:191], v[242:243], 0, s[42:43]
	s_addc_u32 s19, s19, 0
	s_add_i32 s22, s29, s62
	global_load_lds_dwordx4 v[190:191], off
	v_lshl_add_u64 v[190:191], s[18:19], 0, v[130:131]
	s_mov_b32 m0, s22
	s_nop 0
	global_load_lds_dwordx4 v[190:191], off
	v_lshl_add_u64 v[190:191], s[18:19], 0, v[136:137]
	s_add_i32 m0, s22, 0x2000
	s_nop 0
	global_load_lds_dwordx4 v[190:191], off
	v_lshl_add_u64 v[190:191], v[244:245], 0, s[42:43]
	s_mov_b32 m0, s69
	s_nop 0
	global_load_lds_dwordx4 v[190:191], off
	v_lshl_add_u64 v[190:191], v[246:247], 0, s[42:43]
	s_mov_b32 m0, s70
	s_nop 0
	global_load_lds_dwordx4 v[190:191], off
	s_waitcnt vmcnt(8)
	s_waitcnt lgkmcnt(0)
	s_barrier
	s_waitcnt lgkmcnt(0)
	v_mfma_i32_16x16x64_i8 v[30:33], v[150:153], v[182:185], v[30:33]
	v_mfma_i32_16x16x64_i8 v[14:17], v[158:161], v[182:185], v[14:17]
	v_mfma_i32_16x16x64_i8 v[26:29], v[150:153], v[218:221], v[26:29]
	v_mfma_i32_16x16x64_i8 v[10:13], v[158:161], v[218:221], v[10:13]
	v_mfma_i32_16x16x64_i8 v[94:97], v[150:153], v[226:229], v[94:97]
	v_mfma_i32_16x16x64_i8 v[90:93], v[158:161], v[226:229], v[90:93]
	v_mfma_i32_16x16x64_i8 v[86:89], v[150:153], v[234:237], v[86:89]
	v_mfma_i32_16x16x64_i8 v[82:85], v[158:161], v[234:237], v[82:85]
	v_mfma_i32_16x16x64_i8 v[30:33], v[154:157], v[186:189], v[30:33]
	v_mfma_i32_16x16x64_i8 v[14:17], v[162:165], v[186:189], v[14:17]
	v_mfma_i32_16x16x64_i8 v[26:29], v[154:157], v[222:225], v[26:29]
	v_mfma_i32_16x16x64_i8 v[10:13], v[162:165], v[222:225], v[10:13]
	v_mfma_i32_16x16x64_i8 v[94:97], v[154:157], v[230:233], v[94:97]
	v_mfma_i32_16x16x64_i8 v[90:93], v[162:165], v[230:233], v[90:93]
	v_mfma_i32_16x16x64_i8 v[86:89], v[154:157], v[238:241], v[86:89]
	v_mfma_i32_16x16x64_i8 v[82:85], v[162:165], v[238:241], v[82:85]
	v_mfma_i32_16x16x64_i8 v[22:25], v[166:169], v[182:185], v[22:25]
	v_mfma_i32_16x16x64_i8 v[6:9], v[174:177], v[182:185], v[6:9]
	v_mfma_i32_16x16x64_i8 v[18:21], v[166:169], v[218:221], v[18:21]
	v_mfma_i32_16x16x64_i8 v[2:5], v[174:177], v[218:221], v[2:5]
	v_mfma_i32_16x16x64_i8 v[78:81], v[166:169], v[226:229], v[78:81]
	v_mfma_i32_16x16x64_i8 v[74:77], v[174:177], v[226:229], v[74:77]
	v_mfma_i32_16x16x64_i8 v[70:73], v[166:169], v[234:237], v[70:73]
	v_mfma_i32_16x16x64_i8 v[66:69], v[174:177], v[234:237], v[66:69]
	v_mfma_i32_16x16x64_i8 v[22:25], v[170:173], v[186:189], v[22:25]
	v_mfma_i32_16x16x64_i8 v[6:9], v[178:181], v[186:189], v[6:9]
	v_mfma_i32_16x16x64_i8 v[18:21], v[170:173], v[222:225], v[18:21]
	v_mfma_i32_16x16x64_i8 v[2:5], v[178:181], v[222:225], v[2:5]
	v_mfma_i32_16x16x64_i8 v[78:81], v[170:173], v[230:233], v[78:81]
	v_mfma_i32_16x16x64_i8 v[74:77], v[178:181], v[230:233], v[74:77]
	v_mfma_i32_16x16x64_i8 v[70:73], v[170:173], v[238:241], v[70:73]
	v_mfma_i32_16x16x64_i8 v[66:69], v[178:181], v[238:241], v[66:69]
	s_barrier
	s_add_i32 s27, s27, 2
	s_add_u32 s21, s21, 0x100
	s_addc_u32 s26, s26, 0
	s_cmp_gt_u32 s27, 29
	s_mov_b64 s[22:23], s[16:17]
	s_cbranch_scc0 .LBB0_1233
	s_and_b64 vcc, exec, s[44:45]
	s_cbranch_vccz .LBB0_1236
	s_barrier

; #define PG8_STAGE(bufoff, gbase, voff) do { _Pragma("unroll") for (int _i = 0; _i < 2; ++_i) \
;         __builtin_amdgcn_global_load_lds((const unsigned*)((const char*)(gbase) + (voff)[_i]), (PG8_LAS unsigned*)(lds + (bufoff) + ldsw + _i * 8192), 16, 0, 0); } while (0)
; #define PG8_LDA(dst, b, h) do { _Pragma("unroll") for (int m = 0; m < 4; ++m) _Pragma("unroll") for (int k = 0; k < 2; ++k) dst[m][k] = *(const PG8_LAS bf16x8*)(lds + PG8_SA(b, h) + aoff + m * 2048 + k * 1024); } while (0)
; #define PG8_LDB(dst, b, h) do { _Pragma("unroll") for (int n = 0; n < 2; ++n) _Pragma("unroll") for (int k = 0; k < 2; ++k) dst[n][k] = *(const PG8_LAS bf16x8*)(lds + PG8_SB(b, h) + boff + n * 2048 + k * 1024); } while (0)
; #define PG8_WAIT_V(n) asm volatile("s_waitcnt vmcnt(" #n ")" ::: "memory")
; #define PG8_WAIT_L(n) asm volatile("s_waitcnt lgkmcnt(" #n ")" ::: "memory")
; #define PG8_BAR __builtin_amdgcn_s_barrier()
; #define PG8_SCHED __builtin_amdgcn_sched_barrier(0)
; template <class Epi, class Sched, bool ALIGN_EPI = false, bool SP2 = false>
; __device__ __forceinline__ void gemm_phase(PG8_LAS unsigned char* lds, const Gemm g, const Sched& S, const Epi& E) {
;     ...
;             PG8_LDB(B0, 0, 0); PG8_LDB(B1, 0, 1); PG8_SCHED; PG8_LDA(At, 0, 0); PG8_STAGE(PG8_SA(1, 1), a1 + hstep, voffA);
;             PG8_WAIT_V(8); PG8_WAIT_L(0); PG8_BAR; PG8_MMA(0, 0, At, B0); PG8_MMA(0, 1, At, B1); PG8_BAR; PG8_SCHED;
;             PG8_LDA(At, 0, 1); PG8_STAGE(PG8_SB(0, 0), b2, voffB); PG8_STAGE(PG8_SB(0, 1), b2 + hstep, voffB); PG8_STAGE(PG8_SA(0, 0), a2, voffA);
;             PG8_WAIT_V(8); PG8_WAIT_L(0); PG8_BAR; PG8_MMA(1, 0, At, B0); PG8_MMA(1, 1, At, B1); PG8_BAR; PG8_SCHED;
.LBB0_1376:
	ds_read_b128 v[130:133], v182
	ds_read_b128 v[134:137], v182 offset:1024
	ds_read_b128 v[138:141], v182 offset:2048
	ds_read_b128 v[142:145], v182 offset:3072
	ds_read_b128 v[146:149], v183
	ds_read_b128 v[162:165], v183 offset:1024
	ds_read_b128 v[166:169], v183 offset:2048
	ds_read_b128 v[170:173], v183 offset:3072
	s_add_u32 s28, s26, 0xffd50080
	s_addc_u32 s29, s27, -1
	s_cmpk_eq_i32 s54, 0xa8
	s_cselect_b32 s31, s9, s29
	s_cselect_b32 s30, s8, s28
	s_cselect_b32 s29, s25, s33
	s_cselect_b32 s28, s24, s5
	v_lshl_add_u64 v[178:179], s[26:27], 0, v[154:155]
	s_add_i32 m0, s39, 0xc000
	ds_read_b128 v[174:177], v184
	ds_read_b128 v[188:191], v184 offset:1024
	ds_read_b128 v[192:195], v184 offset:2048
	ds_read_b128 v[196:199], v184 offset:3072
	ds_read_b128 v[200:203], v184 offset:4096
	ds_read_b128 v[204:207], v184 offset:5120
	ds_read_b128 v[208:211], v184 offset:6144
	ds_read_b128 v[212:215], v184 offset:7168
	global_load_lds_dwordx4 v[178:179], off
	v_lshl_add_u64 v[178:179], s[26:27], 0, v[156:157]
	s_add_i32 m0, s39, 0xe000
	s_nop 0
	global_load_lds_dwordx4 v[178:179], off
	s_waitcnt vmcnt(8)
	s_waitcnt lgkmcnt(0)
	s_barrier
	s_waitcnt lgkmcnt(0)
	v_mfma_f32_16x16x32_bf16 v[126:129], v[130:133], v[174:177], v[126:129]
	v_mfma_f32_16x16x32_bf16 v[122:125], v[138:141], v[174:177], v[122:125]
	v_mfma_f32_16x16x32_bf16 v[110:113], v[130:133], v[192:195], v[110:113]
	v_mfma_f32_16x16x32_bf16 v[106:109], v[138:141], v[192:195], v[106:109]
	v_mfma_f32_16x16x32_bf16 v[94:97], v[130:133], v[200:203], v[94:97]
	v_mfma_f32_16x16x32_bf16 v[90:93], v[138:141], v[200:203], v[90:93]
	v_mfma_f32_16x16x32_bf16 v[78:81], v[130:133], v[208:211], v[78:81]
	v_mfma_f32_16x16x32_bf16 v[74:77], v[138:141], v[208:211], v[74:77]
	v_mfma_f32_16x16x32_bf16 v[126:129], v[134:137], v[188:191], v[126:129]
	v_mfma_f32_16x16x32_bf16 v[122:125], v[142:145], v[188:191], v[122:125]
	v_mfma_f32_16x16x32_bf16 v[110:113], v[134:137], v[196:199], v[110:113]
	v_mfma_f32_16x16x32_bf16 v[106:109], v[142:145], v[196:199], v[106:109]
	v_mfma_f32_16x16x32_bf16 v[94:97], v[134:137], v[204:207], v[94:97]
	v_mfma_f32_16x16x32_bf16 v[90:93], v[142:145], v[204:207], v[90:93]
	v_mfma_f32_16x16x32_bf16 v[78:81], v[134:137], v[212:215], v[78:81]
	v_mfma_f32_16x16x32_bf16 v[74:77], v[142:145], v[212:215], v[74:77]
	v_mfma_f32_16x16x32_bf16 v[118:121], v[146:149], v[174:177], v[118:121]
	v_mfma_f32_16x16x32_bf16 v[114:117], v[166:169], v[174:177], v[114:117]
	v_mfma_f32_16x16x32_bf16 v[102:105], v[146:149], v[192:195], v[102:105]
	v_mfma_f32_16x16x32_bf16 v[98:101], v[166:169], v[192:195], v[98:101]
	v_mfma_f32_16x16x32_bf16 v[86:89], v[146:149], v[200:203], v[86:89]
	v_mfma_f32_16x16x32_bf16 v[82:85], v[166:169], v[200:203], v[82:85]
	v_mfma_f32_16x16x32_bf16 v[70:73], v[146:149], v[208:211], v[70:73]
	v_mfma_f32_16x16x32_bf16 v[66:69], v[166:169], v[208:211], v[66:69]
	v_mfma_f32_16x16x32_bf16 v[118:121], v[162:165], v[188:191], v[118:121]
	v_mfma_f32_16x16x32_bf16 v[114:117], v[170:173], v[188:191], v[114:117]
	v_mfma_f32_16x16x32_bf16 v[102:105], v[162:165], v[196:199], v[102:105]
	v_mfma_f32_16x16x32_bf16 v[98:101], v[170:173], v[196:199], v[98:101]
	v_mfma_f32_16x16x32_bf16 v[86:89], v[162:165], v[204:207], v[86:89]
	v_mfma_f32_16x16x32_bf16 v[82:85], v[170:173], v[204:207], v[82:85]
	v_mfma_f32_16x16x32_bf16 v[70:73], v[162:165], v[212:215], v[70:73]
	v_mfma_f32_16x16x32_bf16 v[66:69], v[170:173], v[212:215], v[66:69]
	s_barrier
	s_add_i32 s55, s47, s38
	v_lshl_add_u64 v[178:179], s[28:29], 0, v[150:151]
	s_mov_b32 m0, s55
	ds_read_b128 v[174:177], v184 offset:16384
	ds_read_b128 v[188:191], v184 offset:17408
	ds_read_b128 v[192:195], v184 offset:18432
	ds_read_b128 v[196:199], v184 offset:19456
	ds_read_b128 v[200:203], v184 offset:20480
	ds_read_b128 v[204:207], v184 offset:21504
	ds_read_b128 v[208:211], v184 offset:22528
	ds_read_b128 v[212:215], v184 offset:23552
	global_load_lds_dwordx4 v[178:179], off
	s_add_i32 m0, s55, 0x2000
	s_add_u32 s56, s28, 0x2b0000
	v_lshl_add_u64 v[216:217], s[28:29], 0, v[152:153]
	s_addc_u32 s57, s29, 0
	s_add_i32 s55, s48, s38
	global_load_lds_dwordx4 v[216:217], off
	v_lshl_add_u64 v[218:219], s[56:57], 0, v[150:151]
	s_mov_b32 m0, s55
	v_lshl_add_u64 v[220:221], s[30:31], 0, v[152:153]
	global_load_lds_dwordx4 v[218:219], off
	v_lshl_add_u64 v[218:219], s[56:57], 0, v[152:153]
	s_add_i32 m0, s55, 0x2000
	s_nop 0
	global_load_lds_dwordx4 v[218:219], off
	v_lshl_add_u64 v[218:219], s[30:31], 0, v[150:151]
	s_mov_b32 m0, s39
	s_nop 0
	global_load_lds_dwordx4 v[218:219], off
	s_mov_b32 m0, s40
	s_nop 0
	global_load_lds_dwordx4 v[220:221], off
	s_waitcnt vmcnt(8)
	s_waitcnt lgkmcnt(0)
	s_barrier
; #define PG8_STAGE(bufoff, gbase, voff) do { _Pragma("unroll") for (int _i = 0; _i < 2; ++_i) \
;         __builtin_amdgcn_global_load_lds((const unsigned*)((const char*)(gbase) + (voff)[_i]), (PG8_LAS unsigned*)(lds + (bufoff) + ldsw + _i * 8192), 16, 0, 0); } while (0)
; #define PG8_LDA(dst, b, h) do { _Pragma("unroll") for (int m = 0; m < 4; ++m) _Pragma("unroll") for (int k = 0; k < 2; ++k) dst[m][k] = *(const PG8_LAS bf16x8*)(lds + PG8_SA(b, h) + aoff + m * 2048 + k * 1024); } while (0)
; #define PG8_LDB(dst, b, h) do { _Pragma("unroll") for (int n = 0; n < 2; ++n) _Pragma("unroll") for (int k = 0; k < 2; ++k) dst[n][k] = *(const PG8_LAS bf16x8*)(lds + PG8_SB(b, h) + boff + n * 2048 + k * 1024); } while (0)
; #define PG8_WAIT_V(n) asm volatile("s_waitcnt vmcnt(" #n ")" ::: "memory")
; #define PG8_WAIT_L(n) asm volatile("s_waitcnt lgkmcnt(" #n ")" ::: "memory")
; #define PG8_BAR __builtin_amdgcn_s_barrier()
; #define PG8_SCHED __builtin_amdgcn_sched_barrier(0)
; template <class Epi, class Sched, bool ALIGN_EPI = false, bool SP2 = false>
; __device__ __forceinline__ void gemm_phase(PG8_LAS unsigned char* lds, const Gemm g, const Sched& S, const Epi& E) {
;     ...
;             PG8_WAIT_V(8); PG8_WAIT_L(0); PG8_BAR; PG8_MMA(1, 0, At, B0); PG8_MMA(1, 1, At, B1); PG8_BAR; PG8_SCHED;
;             PG8_LDB(B0, 1, 0); PG8_LDB(B1, 1, 1); PG8_SCHED; PG8_LDA(At, 1, 0); PG8_STAGE(PG8_SA(0, 1), a2 + hstep, voffA);
;             PG8_WAIT_V(8); PG8_WAIT_L(0); PG8_BAR; PG8_MMA(0, 0, At, B0); PG8_MMA(0, 1, At, B1); PG8_BAR; PG8_SCHED;
	s_waitcnt lgkmcnt(0)
	v_mfma_f32_16x16x32_bf16 v[62:65], v[130:133], v[174:177], v[62:65]
	v_mfma_f32_16x16x32_bf16 v[58:61], v[138:141], v[174:177], v[58:61]
	v_mfma_f32_16x16x32_bf16 v[46:49], v[130:133], v[192:195], v[46:49]
	v_mfma_f32_16x16x32_bf16 v[42:45], v[138:141], v[192:195], v[42:45]
	v_mfma_f32_16x16x32_bf16 v[30:33], v[130:133], v[200:203], v[30:33]
	v_mfma_f32_16x16x32_bf16 v[26:29], v[138:141], v[200:203], v[26:29]
	v_mfma_f32_16x16x32_bf16 v[14:17], v[130:133], v[208:211], v[14:17]
	v_mfma_f32_16x16x32_bf16 v[10:13], v[138:141], v[208:211], v[10:13]
	v_mfma_f32_16x16x32_bf16 v[62:65], v[134:137], v[188:191], v[62:65]
	v_mfma_f32_16x16x32_bf16 v[58:61], v[142:145], v[188:191], v[58:61]
	v_mfma_f32_16x16x32_bf16 v[46:49], v[134:137], v[196:199], v[46:49]
	v_mfma_f32_16x16x32_bf16 v[42:45], v[142:145], v[196:199], v[42:45]
	v_mfma_f32_16x16x32_bf16 v[30:33], v[134:137], v[204:207], v[30:33]
	v_mfma_f32_16x16x32_bf16 v[26:29], v[142:145], v[204:207], v[26:29]
	v_mfma_f32_16x16x32_bf16 v[14:17], v[134:137], v[212:215], v[14:17]
	v_mfma_f32_16x16x32_bf16 v[10:13], v[142:145], v[212:215], v[10:13]
	v_mfma_f32_16x16x32_bf16 v[54:57], v[146:149], v[174:177], v[54:57]
	v_mfma_f32_16x16x32_bf16 v[50:53], v[166:169], v[174:177], v[50:53]
	v_mfma_f32_16x16x32_bf16 v[38:41], v[146:149], v[192:195], v[38:41]
	v_mfma_f32_16x16x32_bf16 v[34:37], v[166:169], v[192:195], v[34:37]
	v_mfma_f32_16x16x32_bf16 v[22:25], v[146:149], v[200:203], v[22:25]
	v_mfma_f32_16x16x32_bf16 v[18:21], v[166:169], v[200:203], v[18:21]
	v_mfma_f32_16x16x32_bf16 v[6:9], v[146:149], v[208:211], v[6:9]
	v_mfma_f32_16x16x32_bf16 v[2:5], v[166:169], v[208:211], v[2:5]
	v_mfma_f32_16x16x32_bf16 v[54:57], v[162:165], v[188:191], v[54:57]
	v_mfma_f32_16x16x32_bf16 v[50:53], v[170:173], v[188:191], v[50:53]
	v_mfma_f32_16x16x32_bf16 v[38:41], v[162:165], v[196:199], v[38:41]
	v_mfma_f32_16x16x32_bf16 v[34:37], v[170:173], v[196:199], v[34:37]
	v_mfma_f32_16x16x32_bf16 v[22:25], v[162:165], v[204:207], v[22:25]
	v_mfma_f32_16x16x32_bf16 v[18:21], v[170:173], v[204:207], v[18:21]
	v_mfma_f32_16x16x32_bf16 v[6:9], v[162:165], v[212:215], v[6:9]
	v_mfma_f32_16x16x32_bf16 v[2:5], v[170:173], v[212:215], v[2:5]
	s_barrier
	s_add_i32 s55, 0, 0x18000
	s_add_i32 s56, 0, 0x1c000
	v_add_u32_e32 v142, s55, v180
	v_add_u32_e32 v170, s56, v180
	ds_read_b128 v[130:133], v142
	ds_read_b128 v[134:137], v142 offset:1024
	ds_read_b128 v[138:141], v142 offset:2048
	ds_read_b128 v[142:145], v142 offset:3072
	ds_read_b128 v[146:149], v170
	ds_read_b128 v[162:165], v170 offset:1024
	ds_read_b128 v[166:169], v170 offset:2048
	ds_read_b128 v[170:173], v170 offset:3072
	s_add_u32 s30, s30, 0x2b0000
	s_addc_u32 s31, s31, 0
	s_mov_b32 m0, s41
	v_lshl_add_u64 v[222:223], s[30:31], 0, v[150:151]
	ds_read_b128 v[174:177], v184 offset:32768
	ds_read_b128 v[188:191], v184 offset:33792
	ds_read_b128 v[192:195], v184 offset:34816
	ds_read_b128 v[196:199], v184 offset:35840
	ds_read_b128 v[200:203], v184 offset:36864
	ds_read_b128 v[204:207], v184 offset:37888
	ds_read_b128 v[208:211], v184 offset:38912
	ds_read_b128 v[212:215], v184 offset:39936
	global_load_lds_dwordx4 v[222:223], off
	v_lshl_add_u64 v[222:223], s[30:31], 0, v[152:153]
	s_mov_b32 m0, s42
	s_nop 0
	global_load_lds_dwordx4 v[222:223], off
	s_waitcnt vmcnt(8)
	s_waitcnt lgkmcnt(0)
	s_barrier
	s_waitcnt lgkmcnt(0)
	v_mfma_f32_16x16x32_bf16 v[126:129], v[130:133], v[174:177], v[126:129]
	v_mfma_f32_16x16x32_bf16 v[122:125], v[138:141], v[174:177], v[122:125]
	v_mfma_f32_16x16x32_bf16 v[110:113], v[130:133], v[192:195], v[110:113]
	v_mfma_f32_16x16x32_bf16 v[106:109], v[138:141], v[192:195], v[106:109]
	v_mfma_f32_16x16x32_bf16 v[94:97], v[130:133], v[200:203], v[94:97]
	v_mfma_f32_16x16x32_bf16 v[90:93], v[138:141], v[200:203], v[90:93]
	v_mfma_f32_16x16x32_bf16 v[78:81], v[130:133], v[208:211], v[78:81]
	v_mfma_f32_16x16x32_bf16 v[74:77], v[138:141], v[208:211], v[74:77]
	v_mfma_f32_16x16x32_bf16 v[126:129], v[134:137], v[188:191], v[126:129]
	v_mfma_f32_16x16x32_bf16 v[122:125], v[142:145], v[188:191], v[122:125]
	v_mfma_f32_16x16x32_bf16 v[110:113], v[134:137], v[196:199], v[110:113]
	v_mfma_f32_16x16x32_bf16 v[106:109], v[142:145], v[196:199], v[106:109]
	v_mfma_f32_16x16x32_bf16 v[94:97], v[134:137], v[204:207], v[94:97]
	v_mfma_f32_16x16x32_bf16 v[90:93], v[142:145], v[204:207], v[90:93]
	v_mfma_f32_16x16x32_bf16 v[78:81], v[134:137], v[212:215], v[78:81]
	v_mfma_f32_16x16x32_bf16 v[74:77], v[142:145], v[212:215], v[74:77]
	v_mfma_f32_16x16x32_bf16 v[118:121], v[146:149], v[174:177], v[118:121]
	v_mfma_f32_16x16x32_bf16 v[114:117], v[166:169], v[174:177], v[114:117]
	v_mfma_f32_16x16x32_bf16 v[102:105], v[146:149], v[192:195], v[102:105]
	v_mfma_f32_16x16x32_bf16 v[98:101], v[166:169], v[192:195], v[98:101]
	v_mfma_f32_16x16x32_bf16 v[86:89], v[146:149], v[200:203], v[86:89]
	v_mfma_f32_16x16x32_bf16 v[82:85], v[166:169], v[200:203], v[82:85]
	v_mfma_f32_16x16x32_bf16 v[70:73], v[146:149], v[208:211], v[70:73]
	v_mfma_f32_16x16x32_bf16 v[66:69], v[166:169], v[208:211], v[66:69]
	v_mfma_f32_16x16x32_bf16 v[118:121], v[162:165], v[188:191], v[118:121]
	v_mfma_f32_16x16x32_bf16 v[114:117], v[170:173], v[188:191], v[114:117]
	v_mfma_f32_16x16x32_bf16 v[102:105], v[162:165], v[196:199], v[102:105]
	v_mfma_f32_16x16x32_bf16 v[98:101], v[170:173], v[196:199], v[98:101]
	v_mfma_f32_16x16x32_bf16 v[86:89], v[162:165], v[204:207], v[86:89]
	v_mfma_f32_16x16x32_bf16 v[82:85], v[170:173], v[204:207], v[82:85]
	v_mfma_f32_16x16x32_bf16 v[70:73], v[162:165], v[212:215], v[70:73]
	v_mfma_f32_16x16x32_bf16 v[66:69], v[170:173], v[212:215], v[66:69]
	s_barrier
; #define PG8_STAGE(bufoff, gbase, voff) do { _Pragma("unroll") for (int _i = 0; _i < 2; ++_i) \
;         __builtin_amdgcn_global_load_lds((const unsigned*)((const char*)(gbase) + (voff)[_i]), (PG8_LAS unsigned*)(lds + (bufoff) + ldsw + _i * 8192), 16, 0, 0); } while (0)
; #define PG8_LDA(dst, b, h) do { _Pragma("unroll") for (int m = 0; m < 4; ++m) _Pragma("unroll") for (int k = 0; k < 2; ++k) dst[m][k] = *(const PG8_LAS bf16x8*)(lds + PG8_SA(b, h) + aoff + m * 2048 + k * 1024); } while (0)
; #define PG8_WAIT_V(n) asm volatile("s_waitcnt vmcnt(" #n ")" ::: "memory")
; #define PG8_WAIT_L(n) asm volatile("s_waitcnt lgkmcnt(" #n ")" ::: "memory")
; #define PG8_BAR __builtin_amdgcn_s_barrier()
; #define PG8_SCHED __builtin_amdgcn_sched_barrier(0)
; template <class Epi, class Sched, bool ALIGN_EPI = false, bool SP2 = false>
; __device__ __forceinline__ void gemm_phase(PG8_LAS unsigned char* lds, const Gemm g, const Sched& S, const Epi& E) {
;     ...
;             PG8_LDA(At, 1, 1); PG8_STAGE(PG8_SB(1, 0), b3, voffB); PG8_STAGE(PG8_SB(1, 1), b3 + hstep, voffB); PG8_STAGE(PG8_SA(1, 0), a3, voffA);
;             PG8_WAIT_V(8); PG8_WAIT_L(0); PG8_BAR; PG8_MMA(1, 0, At, B0); PG8_MMA(1, 1, At, B1); PG8_BAR; PG8_SCHED;
	s_add_i32 s30, s55, s38
	v_lshl_add_u64 v[178:179], v[178:179], 0, s[20:21]
	s_mov_b32 m0, s30
	ds_read_b128 v[174:177], v184 offset:49152
	ds_read_b128 v[188:191], v184 offset:50176
	ds_read_b128 v[192:195], v184 offset:51200
	ds_read_b128 v[196:199], v184 offset:52224
	ds_read_b128 v[200:203], v184 offset:53248
	ds_read_b128 v[204:207], v184 offset:54272
	ds_read_b128 v[208:211], v184 offset:55296
	ds_read_b128 v[212:215], v184 offset:56320
	global_load_lds_dwordx4 v[178:179], off
	s_add_i32 m0, s30, 0x2000
	s_add_u32 s28, s28, 0x2b0080
	v_lshl_add_u64 v[178:179], v[216:217], 0, s[20:21]
	s_addc_u32 s29, s29, 0
	s_add_i32 s30, s56, s38
	global_load_lds_dwordx4 v[178:179], off
	v_lshl_add_u64 v[178:179], s[28:29], 0, v[150:151]
	s_mov_b32 m0, s30
	s_nop 0
	global_load_lds_dwordx4 v[178:179], off
	v_lshl_add_u64 v[178:179], s[28:29], 0, v[152:153]
	s_add_i32 m0, s30, 0x2000
	s_nop 0
	global_load_lds_dwordx4 v[178:179], off
	v_lshl_add_u64 v[178:179], v[218:219], 0, s[20:21]
	s_mov_b32 m0, s44
	s_nop 0
	global_load_lds_dwordx4 v[178:179], off
	v_lshl_add_u64 v[178:179], v[220:221], 0, s[20:21]
	s_mov_b32 m0, s45
	s_nop 0
	global_load_lds_dwordx4 v[178:179], off
	s_waitcnt vmcnt(8)
	s_waitcnt lgkmcnt(0)
	s_barrier
	s_waitcnt lgkmcnt(0)
	v_mfma_f32_16x16x32_bf16 v[62:65], v[130:133], v[174:177], v[62:65]
	v_mfma_f32_16x16x32_bf16 v[58:61], v[138:141], v[174:177], v[58:61]
	v_mfma_f32_16x16x32_bf16 v[46:49], v[130:133], v[192:195], v[46:49]
	v_mfma_f32_16x16x32_bf16 v[42:45], v[138:141], v[192:195], v[42:45]
	v_mfma_f32_16x16x32_bf16 v[30:33], v[130:133], v[200:203], v[30:33]
	v_mfma_f32_16x16x32_bf16 v[26:29], v[138:141], v[200:203], v[26:29]
	v_mfma_f32_16x16x32_bf16 v[14:17], v[130:133], v[208:211], v[14:17]
	v_mfma_f32_16x16x32_bf16 v[10:13], v[138:141], v[208:211], v[10:13]
	v_mfma_f32_16x16x32_bf16 v[62:65], v[134:137], v[188:191], v[62:65]
	v_mfma_f32_16x16x32_bf16 v[58:61], v[142:145], v[188:191], v[58:61]
	v_mfma_f32_16x16x32_bf16 v[46:49], v[134:137], v[196:199], v[46:49]
	v_mfma_f32_16x16x32_bf16 v[42:45], v[142:145], v[196:199], v[42:45]
	v_mfma_f32_16x16x32_bf16 v[30:33], v[134:137], v[204:207], v[30:33]
	v_mfma_f32_16x16x32_bf16 v[26:29], v[142:145], v[204:207], v[26:29]
	v_mfma_f32_16x16x32_bf16 v[14:17], v[134:137], v[212:215], v[14:17]
	v_mfma_f32_16x16x32_bf16 v[10:13], v[142:145], v[212:215], v[10:13]
	v_mfma_f32_16x16x32_bf16 v[54:57], v[146:149], v[174:177], v[54:57]
	v_mfma_f32_16x16x32_bf16 v[50:53], v[166:169], v[174:177], v[50:53]
	v_mfma_f32_16x16x32_bf16 v[38:41], v[146:149], v[192:195], v[38:41]
	v_mfma_f32_16x16x32_bf16 v[34:37], v[166:169], v[192:195], v[34:37]
	v_mfma_f32_16x16x32_bf16 v[22:25], v[146:149], v[200:203], v[22:25]
	v_mfma_f32_16x16x32_bf16 v[18:21], v[166:169], v[200:203], v[18:21]
	v_mfma_f32_16x16x32_bf16 v[6:9], v[146:149], v[208:211], v[6:9]
	v_mfma_f32_16x16x32_bf16 v[2:5], v[166:169], v[208:211], v[2:5]
	v_mfma_f32_16x16x32_bf16 v[54:57], v[162:165], v[188:191], v[54:57]
	v_mfma_f32_16x16x32_bf16 v[50:53], v[170:173], v[188:191], v[50:53]
	v_mfma_f32_16x16x32_bf16 v[38:41], v[162:165], v[196:199], v[38:41]
	v_mfma_f32_16x16x32_bf16 v[34:37], v[170:173], v[196:199], v[34:37]
	v_mfma_f32_16x16x32_bf16 v[22:25], v[162:165], v[204:207], v[22:25]
	v_mfma_f32_16x16x32_bf16 v[18:21], v[170:173], v[204:207], v[18:21]
	v_mfma_f32_16x16x32_bf16 v[6:9], v[162:165], v[212:215], v[6:9]
	v_mfma_f32_16x16x32_bf16 v[2:5], v[170:173], v[212:215], v[2:5]
	s_barrier
	s_add_i32 s54, s54, 2
	s_add_u32 s26, s26, 0x100
	s_addc_u32 s27, s27, 0
	s_add_u32 s5, s5, 0x100
	s_addc_u32 s33, s33, 0
	s_cmpk_gt_u32 s54, 0xa9
	s_cbranch_scc0 .LBB0_1376
	s_and_b64 vcc, exec, s[22:23]
	s_cbranch_vccz .LBB0_1379
	s_barrier

; #define PG8_STAGE(bufoff, gbase, voff) do { _Pragma("unroll") for (int _i = 0; _i < 2; ++_i) \
;         __builtin_amdgcn_global_load_lds((const unsigned*)((const char*)(gbase) + (voff)[_i]), (PG8_LAS unsigned*)(lds + (bufoff) + ldsw + _i * 8192), 16, 0, 0); } while (0)
; #define PG8_LDA(dst, b, h) do { _Pragma("unroll") for (int m = 0; m < 4; ++m) _Pragma("unroll") for (int k = 0; k < 2; ++k) dst[m][k] = *(const PG8_LAS bf16x8*)(lds + PG8_SA(b, h) + aoff + m * 2048 + k * 1024); } while (0)
; #define PG8_LDB(dst, b, h) do { _Pragma("unroll") for (int n = 0; n < 2; ++n) _Pragma("unroll") for (int k = 0; k < 2; ++k) dst[n][k] = *(const PG8_LAS bf16x8*)(lds + PG8_SB(b, h) + boff + n * 2048 + k * 1024); } while (0)
; #define PG8_WAIT_V(n) asm volatile("s_waitcnt vmcnt(" #n ")" ::: "memory")
; #define PG8_WAIT_L(n) asm volatile("s_waitcnt lgkmcnt(" #n ")" ::: "memory")
; #define PG8_BAR __builtin_amdgcn_s_barrier()
; #define PG8_SCHED __builtin_amdgcn_sched_barrier(0)
; template <class Epi, class Sched, bool ALIGN_EPI = false, bool SP2 = false>
; __device__ __forceinline__ void gemm_phase(PG8_LAS unsigned char* lds, const Gemm g, const Sched& S, const Epi& E) {
;     ...
;             PG8_LDB(B0, 0, 0); PG8_LDB(B1, 0, 1); PG8_SCHED; PG8_LDA(At, 0, 0); PG8_STAGE(PG8_SA(1, 1), a1 + hstep, voffA);
;             PG8_WAIT_V(8); PG8_WAIT_L(0); PG8_BAR; PG8_MMA(0, 0, At, B0); PG8_MMA(0, 1, At, B1); PG8_BAR; PG8_SCHED;
;             PG8_LDA(At, 0, 1); PG8_STAGE(PG8_SB(0, 0), b2, voffB); PG8_STAGE(PG8_SB(0, 1), b2 + hstep, voffB); PG8_STAGE(PG8_SA(0, 0), a2, voffA);
;             PG8_WAIT_V(8); PG8_WAIT_L(0); PG8_BAR; PG8_MMA(1, 0, At, B0); PG8_MMA(1, 1, At, B1); PG8_BAR; PG8_SCHED;
.LBB0_1457:
	ds_read_b128 v[54:57], v200
	ds_read_b128 v[58:61], v200 offset:1024
	ds_read_b128 v[66:69], v200 offset:2048
	ds_read_b128 v[142:145], v200 offset:3072
	ds_read_b128 v[146:149], v201
	ds_read_b128 v[150:153], v201 offset:1024
	ds_read_b128 v[154:157], v201 offset:2048
	ds_read_b128 v[170:173], v201 offset:3072
	s_add_u32 s50, s48, 0xfff80080
	s_addc_u32 s51, s49, -1
	s_cmp_eq_u32 s41, 28
	s_cselect_b32 s53, s1, s51
	s_cselect_b32 s52, s4, s50
	s_cselect_b32 s51, s5, s39
	s_cselect_b32 s50, s11, s33
	v_lshl_add_u64 v[214:215], s[48:49], 0, v[162:163]
	s_add_i32 m0, s47, 0xc000
	ds_read_b128 v[174:177], v202
	ds_read_b128 v[178:181], v202 offset:1024
	ds_read_b128 v[182:185], v202 offset:2048
	ds_read_b128 v[186:189], v202 offset:3072
	ds_read_b128 v[190:193], v202 offset:4096
	ds_read_b128 v[194:197], v202 offset:5120
	ds_read_b128 v[206:209], v202 offset:6144
	ds_read_b128 v[210:213], v202 offset:7168
	global_load_lds_dwordx4 v[214:215], off
	v_lshl_add_u64 v[214:215], s[48:49], 0, v[164:165]
	s_add_i32 m0, s47, 0xe000
	s_nop 0
	global_load_lds_dwordx4 v[214:215], off
	s_waitcnt vmcnt(8)
	s_waitcnt lgkmcnt(0)
	s_barrier
	s_waitcnt lgkmcnt(0)
	v_mfma_i32_16x16x64_i8 v[50:53], v[54:57], v[174:177], v[50:53]
	v_mfma_i32_16x16x64_i8 v[138:141], v[66:69], v[174:177], v[138:141]
	v_mfma_i32_16x16x64_i8 v[126:129], v[54:57], v[182:185], v[126:129]
	v_mfma_i32_16x16x64_i8 v[122:125], v[66:69], v[182:185], v[122:125]
	v_mfma_i32_16x16x64_i8 v[110:113], v[54:57], v[190:193], v[110:113]
	v_mfma_i32_16x16x64_i8 v[106:109], v[66:69], v[190:193], v[106:109]
	v_mfma_i32_16x16x64_i8 v[94:97], v[54:57], v[206:209], v[94:97]
	v_mfma_i32_16x16x64_i8 v[90:93], v[66:69], v[206:209], v[90:93]
	v_mfma_i32_16x16x64_i8 v[50:53], v[58:61], v[178:181], v[50:53]
	v_mfma_i32_16x16x64_i8 v[138:141], v[142:145], v[178:181], v[138:141]
	v_mfma_i32_16x16x64_i8 v[126:129], v[58:61], v[186:189], v[126:129]
	v_mfma_i32_16x16x64_i8 v[122:125], v[142:145], v[186:189], v[122:125]
	v_mfma_i32_16x16x64_i8 v[110:113], v[58:61], v[194:197], v[110:113]
	v_mfma_i32_16x16x64_i8 v[106:109], v[142:145], v[194:197], v[106:109]
	v_mfma_i32_16x16x64_i8 v[94:97], v[58:61], v[210:213], v[94:97]
	v_mfma_i32_16x16x64_i8 v[90:93], v[142:145], v[210:213], v[90:93]
	v_mfma_i32_16x16x64_i8 v[134:137], v[146:149], v[174:177], v[134:137]
	v_mfma_i32_16x16x64_i8 v[130:133], v[154:157], v[174:177], v[130:133]
	v_mfma_i32_16x16x64_i8 v[118:121], v[146:149], v[182:185], v[118:121]
	v_mfma_i32_16x16x64_i8 v[114:117], v[154:157], v[182:185], v[114:117]
	v_mfma_i32_16x16x64_i8 v[102:105], v[146:149], v[190:193], v[102:105]
	v_mfma_i32_16x16x64_i8 v[98:101], v[154:157], v[190:193], v[98:101]
	v_mfma_i32_16x16x64_i8 v[86:89], v[146:149], v[206:209], v[86:89]
	v_mfma_i32_16x16x64_i8 v[82:85], v[154:157], v[206:209], v[82:85]
	v_mfma_i32_16x16x64_i8 v[134:137], v[150:153], v[178:181], v[134:137]
	v_mfma_i32_16x16x64_i8 v[130:133], v[170:173], v[178:181], v[130:133]
	v_mfma_i32_16x16x64_i8 v[118:121], v[150:153], v[186:189], v[118:121]
	v_mfma_i32_16x16x64_i8 v[114:117], v[170:173], v[186:189], v[114:117]
	v_mfma_i32_16x16x64_i8 v[102:105], v[150:153], v[194:197], v[102:105]
	v_mfma_i32_16x16x64_i8 v[98:101], v[170:173], v[194:197], v[98:101]
	v_mfma_i32_16x16x64_i8 v[86:89], v[150:153], v[210:213], v[86:89]
	v_mfma_i32_16x16x64_i8 v[82:85], v[170:173], v[210:213], v[82:85]
	s_barrier
	s_add_i32 s68, s65, s56
	v_lshl_add_u64 v[214:215], s[50:51], 0, v[158:159]
	s_mov_b32 m0, s68
	ds_read_b128 v[174:177], v202 offset:16384
	ds_read_b128 v[178:181], v202 offset:17408
	ds_read_b128 v[182:185], v202 offset:18432
	ds_read_b128 v[186:189], v202 offset:19456
	ds_read_b128 v[190:193], v202 offset:20480
	ds_read_b128 v[194:197], v202 offset:21504
	ds_read_b128 v[206:209], v202 offset:22528
	ds_read_b128 v[210:213], v202 offset:23552
	global_load_lds_dwordx4 v[214:215], off
	s_add_i32 m0, s68, 0x2000
	s_add_u32 s68, s50, 0x80000
	v_lshl_add_u64 v[216:217], s[50:51], 0, v[160:161]
	s_addc_u32 s69, s51, 0
	s_add_i32 s70, s66, s56
	global_load_lds_dwordx4 v[216:217], off
	v_lshl_add_u64 v[218:219], s[68:69], 0, v[158:159]
	s_mov_b32 m0, s70
	v_lshl_add_u64 v[220:221], s[52:53], 0, v[160:161]
	global_load_lds_dwordx4 v[218:219], off
	v_lshl_add_u64 v[218:219], s[68:69], 0, v[160:161]
	s_add_i32 m0, s70, 0x2000
	s_nop 0
	global_load_lds_dwordx4 v[218:219], off
	v_lshl_add_u64 v[218:219], s[52:53], 0, v[158:159]
	s_mov_b32 m0, s47
	s_nop 0
	global_load_lds_dwordx4 v[218:219], off
	s_mov_b32 m0, s57
	s_nop 0
	global_load_lds_dwordx4 v[220:221], off
	s_waitcnt vmcnt(8)
	s_waitcnt lgkmcnt(0)
	s_barrier
; #define PG8_STAGE(bufoff, gbase, voff) do { _Pragma("unroll") for (int _i = 0; _i < 2; ++_i) \
;         __builtin_amdgcn_global_load_lds((const unsigned*)((const char*)(gbase) + (voff)[_i]), (PG8_LAS unsigned*)(lds + (bufoff) + ldsw + _i * 8192), 16, 0, 0); } while (0)
; #define PG8_LDA(dst, b, h) do { _Pragma("unroll") for (int m = 0; m < 4; ++m) _Pragma("unroll") for (int k = 0; k < 2; ++k) dst[m][k] = *(const PG8_LAS bf16x8*)(lds + PG8_SA(b, h) + aoff + m * 2048 + k * 1024); } while (0)
; #define PG8_LDB(dst, b, h) do { _Pragma("unroll") for (int n = 0; n < 2; ++n) _Pragma("unroll") for (int k = 0; k < 2; ++k) dst[n][k] = *(const PG8_LAS bf16x8*)(lds + PG8_SB(b, h) + boff + n * 2048 + k * 1024); } while (0)
; #define PG8_WAIT_V(n) asm volatile("s_waitcnt vmcnt(" #n ")" ::: "memory")
; #define PG8_WAIT_L(n) asm volatile("s_waitcnt lgkmcnt(" #n ")" ::: "memory")
; #define PG8_BAR __builtin_amdgcn_s_barrier()
; #define PG8_SCHED __builtin_amdgcn_sched_barrier(0)
; template <class Epi, class Sched, bool ALIGN_EPI = false, bool SP2 = false>
; __device__ __forceinline__ void gemm_phase(PG8_LAS unsigned char* lds, const Gemm g, const Sched& S, const Epi& E) {
;     ...
;             PG8_WAIT_V(8); PG8_WAIT_L(0); PG8_BAR; PG8_MMA(1, 0, At, B0); PG8_MMA(1, 1, At, B1); PG8_BAR; PG8_SCHED;
;             PG8_LDB(B0, 1, 0); PG8_LDB(B1, 1, 1); PG8_SCHED; PG8_LDA(At, 1, 0); PG8_STAGE(PG8_SA(0, 1), a2 + hstep, voffA);
;             PG8_WAIT_V(8); PG8_WAIT_L(0); PG8_BAR; PG8_MMA(0, 0, At, B0); PG8_MMA(0, 1, At, B1); PG8_BAR; PG8_SCHED;
	s_waitcnt lgkmcnt(0)
	v_mfma_i32_16x16x64_i8 v[78:81], v[54:57], v[174:177], v[78:81]
	v_mfma_i32_16x16x64_i8 v[74:77], v[66:69], v[174:177], v[74:77]
	v_mfma_i32_16x16x64_i8 v[46:49], v[54:57], v[182:185], v[46:49]
	v_mfma_i32_16x16x64_i8 v[42:45], v[66:69], v[182:185], v[42:45]
	v_mfma_i32_16x16x64_i8 v[30:33], v[54:57], v[190:193], v[30:33]
	v_mfma_i32_16x16x64_i8 v[26:29], v[66:69], v[190:193], v[26:29]
	v_mfma_i32_16x16x64_i8 v[14:17], v[54:57], v[206:209], v[14:17]
	v_mfma_i32_16x16x64_i8 v[10:13], v[66:69], v[206:209], v[10:13]
	v_mfma_i32_16x16x64_i8 v[78:81], v[58:61], v[178:181], v[78:81]
	v_mfma_i32_16x16x64_i8 v[74:77], v[142:145], v[178:181], v[74:77]
	v_mfma_i32_16x16x64_i8 v[46:49], v[58:61], v[186:189], v[46:49]
	v_mfma_i32_16x16x64_i8 v[42:45], v[142:145], v[186:189], v[42:45]
	v_mfma_i32_16x16x64_i8 v[30:33], v[58:61], v[194:197], v[30:33]
	v_mfma_i32_16x16x64_i8 v[26:29], v[142:145], v[194:197], v[26:29]
	v_mfma_i32_16x16x64_i8 v[14:17], v[58:61], v[210:213], v[14:17]
	v_mfma_i32_16x16x64_i8 v[10:13], v[142:145], v[210:213], v[10:13]
	v_mfma_i32_16x16x64_i8 v[38:41], v[146:149], v[182:185], v[38:41]
	v_mfma_i32_16x16x64_i8 v[34:37], v[154:157], v[182:185], v[34:37]
	v_mfma_i32_16x16x64_i8 v[22:25], v[146:149], v[190:193], v[22:25]
	v_mfma_i32_16x16x64_i8 v[18:21], v[154:157], v[190:193], v[18:21]
	v_mfma_i32_16x16x64_i8 v[6:9], v[146:149], v[206:209], v[6:9]
	v_mfma_i32_16x16x64_i8 v[2:5], v[154:157], v[206:209], v[2:5]
	v_mfma_i32_16x16x64_i8 v[54:57], v[146:149], v[174:177], v[70:73]
	v_mfma_i32_16x16x64_i8 v[58:61], v[154:157], v[174:177], v[62:65]
	v_mfma_i32_16x16x64_i8 v[38:41], v[150:153], v[186:189], v[38:41]
	v_mfma_i32_16x16x64_i8 v[34:37], v[170:173], v[186:189], v[34:37]
	v_mfma_i32_16x16x64_i8 v[22:25], v[150:153], v[194:197], v[22:25]
	v_mfma_i32_16x16x64_i8 v[18:21], v[170:173], v[194:197], v[18:21]
	v_mfma_i32_16x16x64_i8 v[6:9], v[150:153], v[210:213], v[6:9]
	v_mfma_i32_16x16x64_i8 v[2:5], v[170:173], v[210:213], v[2:5]
	v_mfma_i32_16x16x64_i8 v[54:57], v[150:153], v[178:181], v[54:57]
	v_mfma_i32_16x16x64_i8 v[58:61], v[170:173], v[178:181], v[58:61]
	s_barrier
	s_add_i32 s68, 0, 0x18000
	s_add_i32 s69, 0, 0x1c000
	v_add_u32_e32 v142, s68, v198
	v_add_u32_e32 v170, s69, v198
	ds_read_b128 v[62:65], v142
	ds_read_b128 v[66:69], v142 offset:1024
	ds_read_b128 v[70:73], v142 offset:2048
	ds_read_b128 v[142:145], v142 offset:3072
	ds_read_b128 v[146:149], v170
	ds_read_b128 v[150:153], v170 offset:1024
	ds_read_b128 v[154:157], v170 offset:2048
	ds_read_b128 v[170:173], v170 offset:3072
	s_add_u32 s52, s52, 0x80000
	s_addc_u32 s53, s53, 0
	s_mov_b32 m0, s58
	v_lshl_add_u64 v[222:223], s[52:53], 0, v[158:159]
	ds_read_b128 v[174:177], v202 offset:32768
	ds_read_b128 v[178:181], v202 offset:33792
	ds_read_b128 v[182:185], v202 offset:34816
	ds_read_b128 v[186:189], v202 offset:35840
	ds_read_b128 v[190:193], v202 offset:36864
	ds_read_b128 v[194:197], v202 offset:37888
	ds_read_b128 v[206:209], v202 offset:38912
	ds_read_b128 v[210:213], v202 offset:39936
	global_load_lds_dwordx4 v[222:223], off
	v_lshl_add_u64 v[222:223], s[52:53], 0, v[160:161]
	s_mov_b32 m0, s59
	s_nop 0
	global_load_lds_dwordx4 v[222:223], off
	s_waitcnt vmcnt(8)
	s_waitcnt lgkmcnt(0)
	s_barrier
	s_waitcnt lgkmcnt(0)
	v_mfma_i32_16x16x64_i8 v[50:53], v[62:65], v[174:177], v[50:53]
	v_mfma_i32_16x16x64_i8 v[138:141], v[70:73], v[174:177], v[138:141]
	v_mfma_i32_16x16x64_i8 v[126:129], v[62:65], v[182:185], v[126:129]
	v_mfma_i32_16x16x64_i8 v[122:125], v[70:73], v[182:185], v[122:125]
	v_mfma_i32_16x16x64_i8 v[110:113], v[62:65], v[190:193], v[110:113]
	v_mfma_i32_16x16x64_i8 v[106:109], v[70:73], v[190:193], v[106:109]
	v_mfma_i32_16x16x64_i8 v[94:97], v[62:65], v[206:209], v[94:97]
	v_mfma_i32_16x16x64_i8 v[90:93], v[70:73], v[206:209], v[90:93]
	v_mfma_i32_16x16x64_i8 v[50:53], v[66:69], v[178:181], v[50:53]
	v_mfma_i32_16x16x64_i8 v[138:141], v[142:145], v[178:181], v[138:141]
	v_mfma_i32_16x16x64_i8 v[126:129], v[66:69], v[186:189], v[126:129]
	v_mfma_i32_16x16x64_i8 v[122:125], v[142:145], v[186:189], v[122:125]
	v_mfma_i32_16x16x64_i8 v[110:113], v[66:69], v[194:197], v[110:113]
	v_mfma_i32_16x16x64_i8 v[106:109], v[142:145], v[194:197], v[106:109]
	v_mfma_i32_16x16x64_i8 v[94:97], v[66:69], v[210:213], v[94:97]
	v_mfma_i32_16x16x64_i8 v[90:93], v[142:145], v[210:213], v[90:93]
	v_mfma_i32_16x16x64_i8 v[134:137], v[146:149], v[174:177], v[134:137]
	v_mfma_i32_16x16x64_i8 v[130:133], v[154:157], v[174:177], v[130:133]
	v_mfma_i32_16x16x64_i8 v[118:121], v[146:149], v[182:185], v[118:121]
	v_mfma_i32_16x16x64_i8 v[114:117], v[154:157], v[182:185], v[114:117]
	v_mfma_i32_16x16x64_i8 v[102:105], v[146:149], v[190:193], v[102:105]
	v_mfma_i32_16x16x64_i8 v[98:101], v[154:157], v[190:193], v[98:101]
	v_mfma_i32_16x16x64_i8 v[86:89], v[146:149], v[206:209], v[86:89]
	v_mfma_i32_16x16x64_i8 v[82:85], v[154:157], v[206:209], v[82:85]
	v_mfma_i32_16x16x64_i8 v[134:137], v[150:153], v[178:181], v[134:137]
	v_mfma_i32_16x16x64_i8 v[130:133], v[170:173], v[178:181], v[130:133]
	v_mfma_i32_16x16x64_i8 v[118:121], v[150:153], v[186:189], v[118:121]
	v_mfma_i32_16x16x64_i8 v[114:117], v[170:173], v[186:189], v[114:117]
	v_mfma_i32_16x16x64_i8 v[102:105], v[150:153], v[194:197], v[102:105]
	v_mfma_i32_16x16x64_i8 v[98:101], v[170:173], v[194:197], v[98:101]
	v_mfma_i32_16x16x64_i8 v[86:89], v[150:153], v[210:213], v[86:89]
	v_mfma_i32_16x16x64_i8 v[82:85], v[170:173], v[210:213], v[82:85]
	s_barrier
; #define PG8_STAGE(bufoff, gbase, voff) do { _Pragma("unroll") for (int _i = 0; _i < 2; ++_i) \
;         __builtin_amdgcn_global_load_lds((const unsigned*)((const char*)(gbase) + (voff)[_i]), (PG8_LAS unsigned*)(lds + (bufoff) + ldsw + _i * 8192), 16, 0, 0); } while (0)
; #define PG8_LDA(dst, b, h) do { _Pragma("unroll") for (int m = 0; m < 4; ++m) _Pragma("unroll") for (int k = 0; k < 2; ++k) dst[m][k] = *(const PG8_LAS bf16x8*)(lds + PG8_SA(b, h) + aoff + m * 2048 + k * 1024); } while (0)
; #define PG8_WAIT_V(n) asm volatile("s_waitcnt vmcnt(" #n ")" ::: "memory")
; #define PG8_WAIT_L(n) asm volatile("s_waitcnt lgkmcnt(" #n ")" ::: "memory")
; #define PG8_BAR __builtin_amdgcn_s_barrier()
; #define PG8_SCHED __builtin_amdgcn_sched_barrier(0)
; template <class Epi, class Sched, bool ALIGN_EPI = false, bool SP2 = false>
; __device__ __forceinline__ void gemm_phase(PG8_LAS unsigned char* lds, const Gemm g, const Sched& S, const Epi& E) {
;     ...
;         for (int t = 0; t < nt; t += 2) {
;     ...
;             PG8_LDA(At, 1, 1); PG8_STAGE(PG8_SB(1, 0), b3, voffB); PG8_STAGE(PG8_SB(1, 1), b3 + hstep, voffB); PG8_STAGE(PG8_SA(1, 0), a3, voffA);
;             PG8_WAIT_V(8); PG8_WAIT_L(0); PG8_BAR; PG8_MMA(1, 0, At, B0); PG8_MMA(1, 1, At, B1); PG8_BAR; PG8_SCHED;
	s_add_i32 s52, s68, s56
	v_lshl_add_u64 v[214:215], v[214:215], 0, s[30:31]
	s_mov_b32 m0, s52
	ds_read_b128 v[174:177], v202 offset:49152
	ds_read_b128 v[178:181], v202 offset:50176
	ds_read_b128 v[182:185], v202 offset:51200
	ds_read_b128 v[186:189], v202 offset:52224
	ds_read_b128 v[190:193], v202 offset:53248
	ds_read_b128 v[194:197], v202 offset:54272
	ds_read_b128 v[206:209], v202 offset:55296
	ds_read_b128 v[210:213], v202 offset:56320
	global_load_lds_dwordx4 v[214:215], off
	s_add_i32 m0, s52, 0x2000
	s_add_u32 s50, s50, 0x80080
	v_lshl_add_u64 v[214:215], v[216:217], 0, s[30:31]
	s_addc_u32 s51, s51, 0
	s_add_i32 s52, s69, s56
	global_load_lds_dwordx4 v[214:215], off
	v_lshl_add_u64 v[214:215], s[50:51], 0, v[158:159]
	s_mov_b32 m0, s52
	s_nop 0
	global_load_lds_dwordx4 v[214:215], off
	v_lshl_add_u64 v[214:215], s[50:51], 0, v[160:161]
	s_add_i32 m0, s52, 0x2000
	s_nop 0
	global_load_lds_dwordx4 v[214:215], off
	v_lshl_add_u64 v[214:215], v[218:219], 0, s[30:31]
	s_mov_b32 m0, s61
	s_nop 0
	global_load_lds_dwordx4 v[214:215], off
	v_lshl_add_u64 v[214:215], v[220:221], 0, s[30:31]
	s_mov_b32 m0, s62
	s_nop 0
	global_load_lds_dwordx4 v[214:215], off
	s_waitcnt vmcnt(8)
	s_waitcnt lgkmcnt(0)
	s_barrier
	s_waitcnt lgkmcnt(0)
	v_mfma_i32_16x16x64_i8 v[78:81], v[62:65], v[174:177], v[78:81]
	v_mfma_i32_16x16x64_i8 v[74:77], v[70:73], v[174:177], v[74:77]
	v_mfma_i32_16x16x64_i8 v[46:49], v[62:65], v[182:185], v[46:49]
	v_mfma_i32_16x16x64_i8 v[42:45], v[70:73], v[182:185], v[42:45]
	v_mfma_i32_16x16x64_i8 v[30:33], v[62:65], v[190:193], v[30:33]
	v_mfma_i32_16x16x64_i8 v[26:29], v[70:73], v[190:193], v[26:29]
	v_mfma_i32_16x16x64_i8 v[14:17], v[62:65], v[206:209], v[14:17]
	v_mfma_i32_16x16x64_i8 v[10:13], v[70:73], v[206:209], v[10:13]
	v_mfma_i32_16x16x64_i8 v[78:81], v[66:69], v[178:181], v[78:81]
	v_mfma_i32_16x16x64_i8 v[74:77], v[142:145], v[178:181], v[74:77]
	v_mfma_i32_16x16x64_i8 v[46:49], v[66:69], v[186:189], v[46:49]
	v_mfma_i32_16x16x64_i8 v[42:45], v[142:145], v[186:189], v[42:45]
	v_mfma_i32_16x16x64_i8 v[30:33], v[66:69], v[194:197], v[30:33]
	v_mfma_i32_16x16x64_i8 v[26:29], v[142:145], v[194:197], v[26:29]
	v_mfma_i32_16x16x64_i8 v[14:17], v[66:69], v[210:213], v[14:17]
	v_mfma_i32_16x16x64_i8 v[10:13], v[142:145], v[210:213], v[10:13]
	v_mfma_i32_16x16x64_i8 v[54:57], v[146:149], v[174:177], v[54:57]
	v_mfma_i32_16x16x64_i8 v[70:73], v[150:153], v[178:181], v[54:57]
	v_mfma_i32_16x16x64_i8 v[54:57], v[154:157], v[174:177], v[58:61]
	v_mfma_i32_16x16x64_i8 v[38:41], v[146:149], v[182:185], v[38:41]
	v_mfma_i32_16x16x64_i8 v[34:37], v[154:157], v[182:185], v[34:37]
	v_mfma_i32_16x16x64_i8 v[22:25], v[146:149], v[190:193], v[22:25]
	v_mfma_i32_16x16x64_i8 v[18:21], v[154:157], v[190:193], v[18:21]
	v_mfma_i32_16x16x64_i8 v[6:9], v[146:149], v[206:209], v[6:9]
	v_mfma_i32_16x16x64_i8 v[2:5], v[154:157], v[206:209], v[2:5]
	v_mfma_i32_16x16x64_i8 v[62:65], v[170:173], v[178:181], v[54:57]
	v_mfma_i32_16x16x64_i8 v[38:41], v[150:153], v[186:189], v[38:41]
	v_mfma_i32_16x16x64_i8 v[34:37], v[170:173], v[186:189], v[34:37]
	v_mfma_i32_16x16x64_i8 v[22:25], v[150:153], v[194:197], v[22:25]
	v_mfma_i32_16x16x64_i8 v[18:21], v[170:173], v[194:197], v[18:21]
	v_mfma_i32_16x16x64_i8 v[6:9], v[150:153], v[210:213], v[6:9]
	v_mfma_i32_16x16x64_i8 v[2:5], v[170:173], v[210:213], v[2:5]
	s_barrier
	s_add_i32 s41, s41, 2
	s_add_u32 s48, s48, 0x100
	s_addc_u32 s49, s49, 0
	s_add_u32 s33, s33, 0x100
	s_addc_u32 s39, s39, 0
	s_cmp_gt_u32 s41, 29
	s_cbranch_scc0 .LBB0_1457
	s_and_b64 vcc, exec, s[34:35]
	s_cbranch_vccz .LBB0_1460
	s_barrier
